# v22 plus packed f32 mul/fma in the GEMM epilogues split into scalar pairs (bit-identical)
# baseline (speedup 1.0000x reference)
; __device__ __forceinline__ unsigned cvt_pk_bf16(float lo, float hi) { unsigned r; asm volatile("v_cvt_pk_bf16_f32 %0, %1, %2" : "=v"(r) : "v"(lo), "v"(hi)); return r; }
;     __device__ __forceinline__ void operator()(const f32x4 (&acc)[2][2][4][2], const Unit& u, int wr, int wc, int fr, int fq) const {
;         const int row0 = u.pm * BM + wr * 64 + fr, col0 = u.pn * BM + wc * 32 + 8 * fq;
;         const float sc = (u.pn < 4) ? sA : ((u.pn >= 12 && u.pn < 16) ? sB : 1.f);
; #pragma unroll
;         for (int ai = 0; ai < 2; ++ai)
; #pragma unroll
;             for (int m = 0; m < 4; ++m) { bf16_t* rowp = O + (size_t)(row0 + ai * HALF + m * 16) * ldc + col0;
; #pragma unroll
;                 for (int bj = 0; bj < 2; ++bj) { const f32x4 v0 = acc[ai][bj][m][0] * sc, v1 = acc[ai][bj][m][1] * sc;
;                     u32x4 w; w.x = cvt_pk_bf16(v0[0], v0[1]); w.y = cvt_pk_bf16(v0[2], v0[3]); w.z = cvt_pk_bf16(v1[0], v1[1]); w.w = cvt_pk_bf16(v1[2], v1[3]);
;                     *(u32x4*)(rowp + bj * HALF) = w; } }
.LBB0_137:
	s_and_b32 s13, s57, 0x7ffffffc
	s_cmp_eq_u32 s13, 12
	s_cselect_b64 vcc, -1, 0
	s_cmp_gt_i32 s57, 3
	v_lshl_or_b32 v148, s57, 8, v151
	v_cndmask_b32_e32 v144, 1.0, v155, vcc
	s_cselect_b64 vcc, -1, 0
	v_lshl_add_u32 v157, s20, 8, v145
	v_ashrrev_i32_e32 v149, 31, v148
	v_mov_b64_e32 v[146:147], s[40:41]
	v_cndmask_b32_e32 v144, v156, v144, vcc
	v_mad_i64_i32 v[158:159], s[22:23], v157, s56, v[146:147]
	v_lshlrev_b64 v[148:149], 1, v[148:149]
	v_lshl_add_u64 v[158:159], v[158:159], 0, v[148:149]
	v_mul_f32_e32 v126, v144, v126
	v_mul_f32_e32 v127, v144, v127
	v_mul_f32_e32 v124, v144, v124
	v_mul_f32_e32 v125, v144, v125
	v_mul_f32_e32 v160, v144, v122
	v_mul_f32_e32 v161, v144, v123
	v_mul_f32_e32 v122, v144, v120
	v_mul_f32_e32 v123, v144, v121
	v_cvt_pk_bf16_f32 v120, v124, v125
	v_cvt_pk_bf16_f32 v121, v126, v127
	v_cvt_pk_bf16_f32 v122, v122, v123
	v_cvt_pk_bf16_f32 v123, v160, v161
	global_store_dwordx4 v[158:159], v[120:123], off
	v_mul_f32_e32 v116, v144, v116
	v_mul_f32_e32 v117, v144, v117
	v_mul_f32_e32 v118, v144, v118
	v_mul_f32_e32 v119, v144, v119
	v_mul_f32_e32 v120, v144, v110
	v_mul_f32_e32 v121, v144, v111
	v_mul_f32_e32 v110, v144, v108
	v_mul_f32_e32 v111, v144, v109
	v_cvt_pk_bf16_f32 v108, v116, v117
	v_cvt_pk_bf16_f32 v109, v118, v119
	v_cvt_pk_bf16_f32 v110, v110, v111
	v_cvt_pk_bf16_f32 v111, v120, v121
	global_store_dwordx4 v[158:159], v[108:111], off offset:256
	v_mul_f32_e32 v112, v144, v112
	v_mul_f32_e32 v113, v144, v113
	v_mul_f32_e32 v100, v144, v100
	v_mul_f32_e32 v101, v144, v101
	v_or_b32_e32 v108, 16, v157
	v_mad_i64_i32 v[108:109], s[22:23], v108, s56, v[146:147]
	v_lshl_add_u64 v[108:109], v[108:109], 0, v[148:149]
	v_mul_f32_e32 v110, v144, v114
	v_mul_f32_e32 v111, v144, v115
	v_mul_f32_e32 v114, v144, v106
	v_mul_f32_e32 v115, v144, v107
	v_mul_f32_e32 v106, v144, v104
	v_mul_f32_e32 v107, v144, v105
	v_cvt_pk_bf16_f32 v104, v112, v113
	v_cvt_pk_bf16_f32 v105, v110, v111
	v_cvt_pk_bf16_f32 v106, v106, v107
	v_cvt_pk_bf16_f32 v107, v114, v115
	global_store_dwordx4 v[108:109], v[104:107], off
	v_mul_f32_e32 v102, v144, v102
	v_mul_f32_e32 v103, v144, v103
	v_mul_f32_e32 v96, v144, v96
	v_mul_f32_e32 v97, v144, v97
	v_mul_f32_e32 v104, v144, v94
	v_mul_f32_e32 v105, v144, v95
	v_mul_f32_e32 v94, v144, v92
	v_mul_f32_e32 v95, v144, v93
	v_cvt_pk_bf16_f32 v92, v100, v101
	v_cvt_pk_bf16_f32 v93, v102, v103
	v_cvt_pk_bf16_f32 v94, v94, v95
	v_cvt_pk_bf16_f32 v95, v104, v105
	global_store_dwordx4 v[108:109], v[92:95], off offset:256
	v_mul_f32_e32 v84, v144, v84
	v_mul_f32_e32 v85, v144, v85
	v_mul_f32_e32 v86, v144, v86
	v_mul_f32_e32 v87, v144, v87
	v_or_b32_e32 v92, 32, v157
	v_mad_i64_i32 v[92:93], s[22:23], v92, s56, v[146:147]
	v_lshl_add_u64 v[92:93], v[92:93], 0, v[148:149]
	v_mul_f32_e32 v94, v144, v98
	v_mul_f32_e32 v95, v144, v99
	v_mul_f32_e32 v98, v144, v90
	v_mul_f32_e32 v99, v144, v91
	v_mul_f32_e32 v90, v144, v88
	v_mul_f32_e32 v91, v144, v89
	v_cvt_pk_bf16_f32 v88, v96, v97
	v_cvt_pk_bf16_f32 v89, v94, v95
	v_cvt_pk_bf16_f32 v90, v90, v91
	v_cvt_pk_bf16_f32 v91, v98, v99
	global_store_dwordx4 v[92:93], v[88:91], off
	v_mul_f32_e32 v80, v144, v80
	v_mul_f32_e32 v81, v144, v81
	v_mul_f32_e32 v68, v144, v68
	v_mul_f32_e32 v69, v144, v69
	v_mul_f32_e32 v88, v144, v78
	v_mul_f32_e32 v89, v144, v79
	v_mul_f32_e32 v78, v144, v76
	v_mul_f32_e32 v79, v144, v77
	v_cvt_pk_bf16_f32 v76, v84, v85
	v_cvt_pk_bf16_f32 v77, v86, v87
	v_cvt_pk_bf16_f32 v78, v78, v79
	v_cvt_pk_bf16_f32 v79, v88, v89
	global_store_dwordx4 v[92:93], v[76:79], off offset:256
	v_mul_f32_e32 v70, v144, v70
	v_mul_f32_e32 v71, v144, v71
	v_mul_f32_e32 v62, v144, v62
	v_mul_f32_e32 v63, v144, v63
	v_or_b32_e32 v76, 48, v157
	v_mad_i64_i32 v[76:77], s[22:23], v76, s56, v[146:147]
	v_lshl_add_u64 v[76:77], v[76:77], 0, v[148:149]
	v_mul_f32_e32 v78, v144, v82
	v_mul_f32_e32 v79, v144, v83
	v_mul_f32_e32 v82, v144, v74
	v_mul_f32_e32 v83, v144, v75
	v_mul_f32_e32 v74, v144, v72
	v_mul_f32_e32 v75, v144, v73
	v_cvt_pk_bf16_f32 v72, v80, v81
	v_cvt_pk_bf16_f32 v73, v78, v79
	v_cvt_pk_bf16_f32 v74, v74, v75
	v_cvt_pk_bf16_f32 v75, v82, v83
	global_store_dwordx4 v[76:77], v[72:75], off
	v_mul_f32_e32 v60, v144, v60
	v_mul_f32_e32 v61, v144, v61
	v_mul_f32_e32 v52, v144, v52
; __device__ __forceinline__ unsigned cvt_pk_bf16(float lo, float hi) { unsigned r; asm volatile("v_cvt_pk_bf16_f32 %0, %1, %2" : "=v"(r) : "v"(lo), "v"(hi)); return r; }
; #define PG8_BAR __builtin_amdgcn_s_barrier()
;     __device__ __forceinline__ void operator()(const f32x4 (&acc)[2][2][4][2], const Unit& u, int wr, int wc, int fr, int fq) const {
;     ...
;             for (int m = 0; m < 4; ++m) { bf16_t* rowp = O + (size_t)(row0 + ai * HALF + m * 16) * ldc + col0;
; #pragma unroll
;                 for (int bj = 0; bj < 2; ++bj) { const f32x4 v0 = acc[ai][bj][m][0] * sc, v1 = acc[ai][bj][m][1] * sc;
;                     u32x4 w; w.x = cvt_pk_bf16(v0[0], v0[1]); w.y = cvt_pk_bf16(v0[2], v0[3]); w.z = cvt_pk_bf16(v1[0], v1[1]); w.w = cvt_pk_bf16(v1[2], v1[3]);
;                     *(u32x4*)(rowp + bj * HALF) = w; } }
; template <class Epi, class Sched, bool ALIGN_EPI = false, bool SP2 = false>
; __device__ __forceinline__ void gemm_phase(PG8_LAS unsigned char* lds, const Gemm g, const Sched& S, const Epi& E) {
;     ...
;         if constexpr (!Epi::AFTER_DRAIN) { E(acc, cur, wr, wc, fr, fq); S.done(cur); }
;         if (!has_next) break;
; #pragma unroll
;         for (int a = 0; a < 2; ++a)
; #pragma unroll
;             for (int b = 0; b < 2; ++b)
; #pragma unroll
;                 for (int m = 0; m < 4; ++m)
; #pragma unroll
;                     for (int n = 0; n < 2; ++n) acc[a][b][m][n] = (f32x4){0.f, 0.f, 0.f, 0.f};
;         cur = nxt; cA = nA; cB = nB; ++ui;
;         if constexpr (ALIGN_EPI) { if (wr == 1) PG8_BAR; }
	v_mul_f32_e32 v53, v144, v53
	v_mul_f32_e32 v72, v144, v66
	v_mul_f32_e32 v73, v144, v67
	v_mul_f32_e32 v66, v144, v64
	v_mul_f32_e32 v67, v144, v65
	v_cvt_pk_bf16_f32 v64, v68, v69
	v_cvt_pk_bf16_f32 v65, v70, v71
	v_cvt_pk_bf16_f32 v66, v66, v67
	v_cvt_pk_bf16_f32 v67, v72, v73
	global_store_dwordx4 v[76:77], v[64:67], off offset:256
	v_mul_f32_e32 v54, v144, v54
	v_mul_f32_e32 v55, v144, v55
	v_mul_f32_e32 v48, v144, v48
	v_mul_f32_e32 v49, v144, v49
	v_add_u32_e32 v64, 0x80, v157
	v_mad_i64_i32 v[64:65], s[22:23], v64, s56, v[146:147]
	v_lshl_add_u64 v[64:65], v[64:65], 0, v[148:149]
	v_mul_f32_e32 v66, v144, v58
	v_mul_f32_e32 v67, v144, v59
	v_mul_f32_e32 v58, v144, v56
	v_mul_f32_e32 v59, v144, v57
	v_cvt_pk_bf16_f32 v56, v60, v61
	v_cvt_pk_bf16_f32 v57, v62, v63
	v_cvt_pk_bf16_f32 v58, v58, v59
	v_cvt_pk_bf16_f32 v59, v66, v67
	global_store_dwordx4 v[64:65], v[56:59], off
	v_mul_f32_e32 v36, v144, v36
	v_mul_f32_e32 v37, v144, v37
	v_mul_f32_e32 v38, v144, v38
	v_mul_f32_e32 v39, v144, v39
	v_mul_f32_e32 v56, v144, v46
	v_mul_f32_e32 v57, v144, v47
	v_mul_f32_e32 v46, v144, v44
	v_mul_f32_e32 v47, v144, v45
	v_cvt_pk_bf16_f32 v44, v52, v53
	v_cvt_pk_bf16_f32 v45, v54, v55
	v_cvt_pk_bf16_f32 v46, v46, v47
	v_cvt_pk_bf16_f32 v47, v56, v57
	global_store_dwordx4 v[64:65], v[44:47], off offset:256
	v_mul_f32_e32 v32, v144, v32
	v_mul_f32_e32 v33, v144, v33
	v_mul_f32_e32 v20, v144, v20
	v_mul_f32_e32 v21, v144, v21
	v_add_u32_e32 v44, 0x90, v157
	v_mad_i64_i32 v[44:45], s[22:23], v44, s56, v[146:147]
	v_lshl_add_u64 v[44:45], v[44:45], 0, v[148:149]
	v_mul_f32_e32 v46, v144, v50
	v_mul_f32_e32 v47, v144, v51
	v_mul_f32_e32 v50, v144, v42
	v_mul_f32_e32 v51, v144, v43
	v_mul_f32_e32 v42, v144, v40
	v_mul_f32_e32 v43, v144, v41
	v_cvt_pk_bf16_f32 v40, v48, v49
	v_cvt_pk_bf16_f32 v41, v46, v47
	v_cvt_pk_bf16_f32 v42, v42, v43
	v_cvt_pk_bf16_f32 v43, v50, v51
	global_store_dwordx4 v[44:45], v[40:43], off
	v_mul_f32_e32 v22, v144, v22
	v_mul_f32_e32 v23, v144, v23
	v_mul_f32_e32 v16, v144, v16
	v_mul_f32_e32 v17, v144, v17
	v_mul_f32_e32 v40, v144, v30
	v_mul_f32_e32 v41, v144, v31
	v_mul_f32_e32 v30, v144, v28
	v_mul_f32_e32 v31, v144, v29
	v_cvt_pk_bf16_f32 v28, v36, v37
	v_cvt_pk_bf16_f32 v29, v38, v39
	v_cvt_pk_bf16_f32 v30, v30, v31
	v_cvt_pk_bf16_f32 v31, v40, v41
	global_store_dwordx4 v[44:45], v[28:31], off offset:256
	s_andn2_b64 vcc, exec, s[0:1]
	s_mov_b64 s[0:1], -1
	v_add_u32_e32 v28, 0xa0, v157
	v_mad_i64_i32 v[28:29], s[22:23], v28, s56, v[146:147]
	v_lshl_add_u64 v[28:29], v[28:29], 0, v[148:149]
	v_mul_f32_e32 v30, v144, v34
	v_mul_f32_e32 v31, v144, v35
	v_mul_f32_e32 v34, v144, v26
	v_mul_f32_e32 v35, v144, v27
	v_mul_f32_e32 v26, v144, v24
	v_mul_f32_e32 v27, v144, v25
	v_cvt_pk_bf16_f32 v24, v32, v33
	v_cvt_pk_bf16_f32 v25, v30, v31
	v_cvt_pk_bf16_f32 v26, v26, v27
	v_cvt_pk_bf16_f32 v27, v34, v35
	global_store_dwordx4 v[28:29], v[24:27], off
	v_mul_f32_e32 v6, v144, v6
	v_mul_f32_e32 v7, v144, v7
	v_mul_f32_e32 v4, v144, v4
	v_mul_f32_e32 v5, v144, v5
	v_mul_f32_e32 v24, v144, v14
	v_mul_f32_e32 v25, v144, v15
	v_mul_f32_e32 v14, v144, v12
	v_mul_f32_e32 v15, v144, v13
	v_cvt_pk_bf16_f32 v12, v20, v21
	v_cvt_pk_bf16_f32 v13, v22, v23
	v_cvt_pk_bf16_f32 v14, v14, v15
	v_cvt_pk_bf16_f32 v15, v24, v25
	global_store_dwordx4 v[28:29], v[12:15], off offset:256
	s_nop 1
	v_add_u32_e32 v12, 0xb0, v157
	v_mad_i64_i32 v[12:13], s[22:23], v12, s56, v[146:147]
	v_lshl_add_u64 v[12:13], v[12:13], 0, v[148:149]
	v_mul_f32_e32 v14, v144, v18
	v_mul_f32_e32 v15, v144, v19
	v_mul_f32_e32 v18, v144, v10
	v_mul_f32_e32 v19, v144, v11
	v_mul_f32_e32 v10, v144, v8
	v_mul_f32_e32 v11, v144, v9
	v_cvt_pk_bf16_f32 v8, v16, v17
	v_cvt_pk_bf16_f32 v9, v14, v15
	v_cvt_pk_bf16_f32 v10, v10, v11
	v_cvt_pk_bf16_f32 v11, v18, v19
	global_store_dwordx4 v[12:13], v[8:11], off
	s_nop 1
	v_mul_f32_e32 v8, v144, v2
	v_mul_f32_e32 v9, v144, v3
	v_mul_f32_e32 v2, v144, v0
	v_mul_f32_e32 v3, v144, v1
	v_cvt_pk_bf16_f32 v0, v4, v5
	v_cvt_pk_bf16_f32 v1, v6, v7
	v_cvt_pk_bf16_f32 v2, v2, v3
	v_cvt_pk_bf16_f32 v3, v8, v9
	global_store_dwordx4 v[12:13], v[0:3], off offset:256
	s_cbranch_vccnz .LBB0_130
	s_andn2_b64 vcc, exec, s[6:7]
	s_cbranch_vccnz .LBB0_129
	s_barrier
	s_branch .LBB0_129

; #define LDS_WAIT() asm volatile("s_waitcnt lgkmcnt(0)" ::: "memory")
; __device__ __forceinline__ int crow(int r, int hi) { return (r & 3) + 8 * (r >> 2) + 4 * hi; }
; __device__ __forceinline__ float half_max(float v) { auto rr = __builtin_amdgcn_permlane32_swap(__float_as_uint(v), __float_as_uint(v), false, false); return fmaxf(__uint_as_float(rr[0]), __uint_as_float(rr[1])); }
; __device__ __forceinline__ float half_add(float v) { auto rr = __builtin_amdgcn_permlane32_swap(__float_as_uint(v), __float_as_uint(v), false, false); return __uint_as_float(rr[0]) + __uint_as_float(rr[1]); }
; template <int MODE>
; __device__ __forceinline__ void phase(LAS unsigned char* lds, const bf16* __restrict__ PROJ, bf16* __restrict__ MIXED, const float* __restrict__ tbA_g, const float* __restrict__ norm_a_g, bf16* PO, float* PML, int G, int vcu) {
;     ...
;             float pmax = p[0];
; #pragma unroll
;             for (int i = 1; i < 16; ++i) pmax = fmaxf(pmax, p[i]);
;             pmax = half_max(pmax);
;             float mn, alpha;
;             if (__all(pmax - m_reg <= 8.f)) { mn = m_reg; alpha = 1.f; }
;             else { mn = fmaxf(m_reg, pmax); alpha = __builtin_amdgcn_exp2f(m_reg - mn); m_reg = mn; }
;             float ps = 0.f;
; #pragma unroll
;             for (int i = 0; i < 16; ++i) { p[i] = __builtin_amdgcn_exp2f(p[i] - mn); ps += p[i]; }
;             ps = half_add(ps);
;             l_reg = l_reg * alpha + ps;
;             if (__any(alpha < 1.f)) { if (hi == 0) al_l[r32] = alpha; LDS_WAIT();
; #pragma unroll
;                 for (int i = 0; i < 16; ++i) { const float a = al_l[crow(i, hi)];
; #pragma unroll
;                     for (int d = 0; d < 4; ++d) o[d][i] *= a; } }
.LBB0_216:
	v_max_f32_e32 v78, v113, v113
	v_max_f32_e32 v79, v112, v112
	v_max_f32_e32 v78, v79, v78
	v_max3_f32 v78, v78, v66, v67
	v_max3_f32 v78, v78, v68, v69
	v_max3_f32 v78, v78, v70, v71
	v_max3_f32 v78, v78, v72, v73
	v_max3_f32 v78, v78, v74, v75
	v_max3_f32 v78, v78, v76, v77
	v_max3_f32 v78, v78, v64, v65
	v_mov_b32_e32 v79, v78
	s_nop 1
	v_permlane32_swap_b32_e32 v78, v79
	v_max_f32_e32 v79, v79, v79
	v_max_f32_e32 v78, v78, v78
	v_max_f32_e32 v78, v78, v79
	v_sub_f32_e32 v79, v78, v221
	v_cmp_ge_f32_e32 vcc, s51, v79
	s_cmp_eq_u64 vcc, exec
	v_max_f32_e32 v79, v221, v221
	v_max_f32_e32 v78, v79, v78
	s_cselect_b64 vcc, -1, 0
	v_sub_f32_e32 v79, v221, v78
	v_cndmask_b32_e32 v221, v78, v221, vcc
	v_sub_f32_e32 v78, v112, v221
	v_exp_f32_e32 v114, v79
	v_exp_f32_e32 v78, v78
	v_sub_f32_e32 v79, v113, v221
	v_exp_f32_e32 v79, v79
	v_sub_f32_e32 v66, v66, v221
	v_exp_f32_e32 v66, v66
	v_sub_f32_e32 v67, v67, v221
	v_exp_f32_e32 v67, v67
	v_sub_f32_e32 v68, v68, v221
	v_add_f32_e32 v112, 0, v78
	v_exp_f32_e32 v68, v68
	v_sub_f32_e32 v69, v69, v221
	v_add_f32_e32 v112, v79, v112
	v_exp_f32_e32 v69, v69
	v_sub_f32_e32 v70, v70, v221
	v_add_f32_e32 v112, v66, v112
	v_exp_f32_e32 v70, v70
	v_sub_f32_e32 v71, v71, v221
	v_add_f32_e32 v113, v67, v112
	v_exp_f32_e32 v112, v71
	v_add_f32_e32 v71, v68, v113
	v_add_f32_e32 v71, v69, v71
	v_add_f32_e32 v71, v70, v71
	v_add_f32_e32 v113, v112, v71
	v_sub_f32_e32 v71, v72, v221
	v_exp_f32_e32 v71, v71
	v_sub_f32_e32 v72, v73, v221
	v_exp_f32_e32 v72, v72
	v_sub_f32_e32 v73, v74, v221
	v_exp_f32_e32 v73, v73
	v_sub_f32_e32 v74, v75, v221
	v_exp_f32_e32 v74, v74
	v_add_f32_e32 v75, v71, v113
	v_add_f32_e32 v75, v72, v75
	v_add_f32_e32 v75, v73, v75
	v_add_f32_e32 v113, v74, v75
	v_sub_f32_e32 v75, v76, v221
	v_exp_f32_e32 v75, v75
	v_sub_f32_e32 v76, v77, v221
	v_exp_f32_e32 v76, v76
	v_sub_f32_e32 v64, v64, v221
	v_exp_f32_e32 v64, v64
	v_sub_f32_e32 v65, v65, v221
	v_exp_f32_e32 v65, v65
	v_add_f32_e32 v77, v75, v113
	v_add_f32_e32 v77, v76, v77
	v_add_f32_e32 v77, v64, v77
	v_add_f32_e32 v226, v65, v77
	v_cndmask_b32_e64 v225, v114, 1.0, vcc
	v_mov_b32_e32 v227, v226
	s_nop 1
	v_permlane32_swap_b32_e32 v226, v227
	v_cmp_gt_f32_e32 vcc, 1.0, v225
	s_cbranch_vccz .LBB0_220
	s_and_saveexec_b64 s[4:5], s[0:1]
	ds_write_b32 v173, v225 offset:128
	s_or_b64 exec, exec, s[4:5]
	s_waitcnt lgkmcnt(0)
	ds_read_b128 v[114:117], v175 offset:224
	ds_read_b128 v[118:121], v175 offset:192
	ds_read_b128 v[122:125], v175 offset:160
	ds_read_b128 v[126:129], v175 offset:128
	s_waitcnt lgkmcnt(3)
	v_mul_f32_e32 v62, v62, v116
	v_mul_f32_e32 v63, v63, v117
	s_waitcnt lgkmcnt(2)
	v_mul_f32_e32 v58, v58, v120
	v_mul_f32_e32 v59, v59, v121
	s_waitcnt lgkmcnt(1)
	v_mul_f32_e32 v54, v54, v124
	v_mul_f32_e32 v55, v55, v125
	s_waitcnt lgkmcnt(0)
	v_mul_f32_e32 v50, v50, v128
	v_mul_f32_e32 v51, v51, v129
	v_mul_f32_e32 v60, v60, v114
	v_mul_f32_e32 v61, v61, v115
	v_mul_f32_e32 v56, v56, v118
	v_mul_f32_e32 v57, v57, v119
	v_mul_f32_e32 v52, v52, v122
	v_mul_f32_e32 v53, v53, v123
	v_mul_f32_e32 v48, v48, v126
	v_mul_f32_e32 v49, v49, v127
	v_mul_f32_e32 v46, v46, v116
	v_mul_f32_e32 v47, v47, v117
	v_mul_f32_e32 v42, v42, v120
	v_mul_f32_e32 v43, v43, v121
	v_mul_f32_e32 v38, v38, v124
	v_mul_f32_e32 v39, v39, v125
	v_mul_f32_e32 v34, v34, v128
	v_mul_f32_e32 v35, v35, v129
	v_mul_f32_e32 v44, v44, v114
	v_mul_f32_e32 v45, v45, v115
	v_mul_f32_e32 v40, v40, v118
	v_mul_f32_e32 v41, v41, v119
	v_mul_f32_e32 v36, v36, v122
	v_mul_f32_e32 v37, v37, v123
	v_mul_f32_e32 v32, v32, v126
	v_mul_f32_e32 v33, v33, v127
	v_mul_f32_e32 v30, v30, v116
	v_mul_f32_e32 v31, v31, v117
	v_mul_f32_e32 v26, v26, v120
	v_mul_f32_e32 v27, v27, v121
	v_mul_f32_e32 v22, v22, v124
	v_mul_f32_e32 v23, v23, v125
	v_mul_f32_e32 v18, v18, v128
	v_mul_f32_e32 v19, v19, v129
	v_mul_f32_e32 v28, v28, v114
	v_mul_f32_e32 v29, v29, v115
	v_mul_f32_e32 v24, v24, v118
	v_mul_f32_e32 v25, v25, v119
	v_mul_f32_e32 v20, v20, v122
	v_mul_f32_e32 v21, v21, v123
	v_mul_f32_e32 v16, v16, v126
	v_mul_f32_e32 v17, v17, v127
	v_mul_f32_e32 v14, v14, v116
	v_mul_f32_e32 v15, v15, v117
	v_mul_f32_e32 v10, v10, v120
	v_mul_f32_e32 v11, v11, v121
	v_mul_f32_e32 v6, v6, v124
	v_mul_f32_e32 v7, v7, v125
	v_mul_f32_e32 v2, v2, v128
	v_mul_f32_e32 v3, v3, v129
	v_mul_f32_e32 v12, v12, v114
	v_mul_f32_e32 v13, v13, v115
	v_mul_f32_e32 v8, v8, v118
	v_mul_f32_e32 v9, v9, v119
	v_mul_f32_e32 v4, v4, v122
	v_mul_f32_e32 v5, v5, v123
	v_mul_f32_e32 v0, v0, v126
	v_mul_f32_e32 v1, v1, v127

; #define LDS_WAIT() asm volatile("s_waitcnt lgkmcnt(0)" ::: "memory")
; __device__ __forceinline__ int crow(int r, int hi) { return (r & 3) + 8 * (r >> 2) + 4 * hi; }
; __device__ __forceinline__ float half_max(float v) { auto rr = __builtin_amdgcn_permlane32_swap(__float_as_uint(v), __float_as_uint(v), false, false); return fmaxf(__uint_as_float(rr[0]), __uint_as_float(rr[1])); }
; __device__ __forceinline__ float half_add(float v) { auto rr = __builtin_amdgcn_permlane32_swap(__float_as_uint(v), __float_as_uint(v), false, false); return __uint_as_float(rr[0]) + __uint_as_float(rr[1]); }
; template <int MODE>
; __device__ __forceinline__ void phase(LAS unsigned char* lds, const bf16* __restrict__ PROJ, bf16* __restrict__ MIXED, const float* __restrict__ tbA_g, const float* __restrict__ norm_a_g, bf16* PO, float* PML, int G, int vcu) {
;     ...
;             float pmax = p[0];
; #pragma unroll
;             for (int i = 1; i < 16; ++i) pmax = fmaxf(pmax, p[i]);
;             pmax = half_max(pmax);
;             float mn, alpha;
;             if (__all(pmax - m_reg <= 8.f)) { mn = m_reg; alpha = 1.f; }
;             else { mn = fmaxf(m_reg, pmax); alpha = __builtin_amdgcn_exp2f(m_reg - mn); m_reg = mn; }
;             float ps = 0.f;
; #pragma unroll
;             for (int i = 0; i < 16; ++i) { p[i] = __builtin_amdgcn_exp2f(p[i] - mn); ps += p[i]; }
;             ps = half_add(ps);
;             l_reg = l_reg * alpha + ps;
;             if (__any(alpha < 1.f)) { if (hi == 0) al_l[r32] = alpha; LDS_WAIT();
; #pragma unroll
;                 for (int i = 0; i < 16; ++i) { const float a = al_l[crow(i, hi)];
; #pragma unroll
;                     for (int d = 0; d < 4; ++d) o[d][i] *= a; } }
.LBB0_240:
	v_max_f32_e32 v64, v81, v81
	v_max_f32_e32 v65, v80, v80
	v_max_f32_e32 v64, v65, v64
	v_max3_f32 v64, v64, v66, v67
	v_max3_f32 v64, v64, v68, v69
	v_max3_f32 v64, v64, v70, v71
	v_max3_f32 v64, v64, v72, v73
	v_max3_f32 v64, v64, v74, v75
	v_max3_f32 v64, v64, v76, v77
	v_max3_f32 v64, v64, v78, v79
	v_mov_b32_e32 v65, v64
	s_nop 1
	v_permlane32_swap_b32_e32 v64, v65
	v_max_f32_e32 v65, v65, v65
	v_max_f32_e32 v64, v64, v64
	v_max_f32_e32 v64, v64, v65
	v_sub_f32_e32 v65, v64, v221
	v_cmp_ge_f32_e32 vcc, s51, v65
	s_cmp_eq_u64 vcc, exec
	v_max_f32_e32 v65, v221, v221
	v_max_f32_e32 v64, v65, v64
	s_cselect_b64 vcc, -1, 0
	v_sub_f32_e32 v65, v221, v64
	v_cndmask_b32_e32 v64, v64, v221, vcc
	v_exp_f32_e32 v85, v65
	v_sub_f32_e32 v65, v80, v64
	v_exp_f32_e32 v80, v65
	v_sub_f32_e32 v65, v81, v64
	v_exp_f32_e32 v81, v65
	v_sub_f32_e32 v65, v66, v64
	v_exp_f32_e32 v82, v65
	v_sub_f32_e32 v65, v67, v64
	v_exp_f32_e32 v83, v65
	v_sub_f32_e32 v66, v68, v64
	v_add_f32_e32 v65, 0, v80
	v_exp_f32_e32 v68, v66
	v_sub_f32_e32 v66, v69, v64
	v_add_f32_e32 v65, v81, v65
	v_exp_f32_e32 v69, v66
	v_sub_f32_e32 v66, v70, v64
	v_add_f32_e32 v65, v82, v65
	v_exp_f32_e32 v70, v66
	v_sub_f32_e32 v66, v71, v64
	v_add_f32_e32 v65, v83, v65
	v_exp_f32_e32 v84, v66
	v_sub_f32_e32 v66, v72, v64
	v_add_f32_e32 v65, v68, v65
	v_exp_f32_e32 v71, v66
	v_sub_f32_e32 v66, v73, v64
	v_add_f32_e32 v65, v69, v65
	v_exp_f32_e32 v72, v66
	v_sub_f32_e32 v66, v74, v64
	v_add_f32_e32 v65, v70, v65
	v_exp_f32_e32 v73, v66
	v_sub_f32_e32 v66, v75, v64
	v_add_f32_e32 v65, v84, v65
	v_exp_f32_e32 v74, v66
	v_sub_f32_e32 v66, v76, v64
	v_add_f32_e32 v65, v71, v65
	v_exp_f32_e32 v75, v66
	v_sub_f32_e32 v66, v77, v64
	v_add_f32_e32 v65, v72, v65
	v_exp_f32_e32 v76, v66
	v_sub_f32_e32 v66, v78, v64
	v_add_f32_e32 v65, v73, v65
	v_exp_f32_e32 v77, v66
	v_sub_f32_e32 v66, v79, v64
	v_add_f32_e32 v65, v74, v65
	v_exp_f32_e32 v78, v66
	v_add_f32_e32 v65, v75, v65
	v_add_f32_e32 v65, v76, v65
	v_add_f32_e32 v65, v77, v65
	v_add_f32_e32 v65, v78, v65
	v_cndmask_b32_e64 v66, v85, 1.0, vcc
	v_mov_b32_e32 v67, v65
	s_nop 1
	v_permlane32_swap_b32_e32 v65, v67
	v_cmp_gt_f32_e32 vcc, 1.0, v66
	s_cbranch_vccz .LBB0_244
	s_and_saveexec_b64 s[4:5], s[0:1]
	ds_write_b32 v173, v66 offset:128
	s_or_b64 exec, exec, s[4:5]
	s_waitcnt lgkmcnt(0)
	ds_read_b128 v[86:89], v175 offset:224
	ds_read_b128 v[90:93], v175 offset:192
	ds_read_b128 v[94:97], v175 offset:160
	ds_read_b128 v[98:101], v175 offset:128
	s_waitcnt lgkmcnt(3)
	v_mul_f32_e32 v62, v62, v88
	v_mul_f32_e32 v63, v63, v89
	s_waitcnt lgkmcnt(2)
	v_mul_f32_e32 v58, v58, v92
	v_mul_f32_e32 v59, v59, v93
	s_waitcnt lgkmcnt(1)
	v_mul_f32_e32 v54, v54, v96
	v_mul_f32_e32 v55, v55, v97
	s_waitcnt lgkmcnt(0)
	v_mul_f32_e32 v50, v50, v100
	v_mul_f32_e32 v51, v51, v101
	v_mul_f32_e32 v60, v60, v86
	v_mul_f32_e32 v61, v61, v87
	v_mul_f32_e32 v56, v56, v90
	v_mul_f32_e32 v57, v57, v91
	v_mul_f32_e32 v52, v52, v94
	v_mul_f32_e32 v53, v53, v95
	v_mul_f32_e32 v48, v48, v98
	v_mul_f32_e32 v49, v49, v99
	v_mul_f32_e32 v46, v46, v88
	v_mul_f32_e32 v47, v47, v89
	v_mul_f32_e32 v42, v42, v92
	v_mul_f32_e32 v43, v43, v93
	v_mul_f32_e32 v38, v38, v96
	v_mul_f32_e32 v39, v39, v97
	v_mul_f32_e32 v34, v34, v100
	v_mul_f32_e32 v35, v35, v101
	v_mul_f32_e32 v44, v44, v86
	v_mul_f32_e32 v45, v45, v87
	v_mul_f32_e32 v40, v40, v90
	v_mul_f32_e32 v41, v41, v91
	v_mul_f32_e32 v36, v36, v94
	v_mul_f32_e32 v37, v37, v95
	v_mul_f32_e32 v32, v32, v98
	v_mul_f32_e32 v33, v33, v99
	v_mul_f32_e32 v30, v30, v88
	v_mul_f32_e32 v31, v31, v89
	v_mul_f32_e32 v26, v26, v92
	v_mul_f32_e32 v27, v27, v93
	v_mul_f32_e32 v22, v22, v96
	v_mul_f32_e32 v23, v23, v97
	v_mul_f32_e32 v18, v18, v100
	v_mul_f32_e32 v19, v19, v101
	v_mul_f32_e32 v28, v28, v86
	v_mul_f32_e32 v29, v29, v87
	v_mul_f32_e32 v24, v24, v90
	v_mul_f32_e32 v25, v25, v91
	v_mul_f32_e32 v20, v20, v94
	v_mul_f32_e32 v21, v21, v95
	v_mul_f32_e32 v16, v16, v98
	v_mul_f32_e32 v17, v17, v99
	v_mul_f32_e32 v14, v14, v88
	v_mul_f32_e32 v15, v15, v89
	v_mul_f32_e32 v10, v10, v92
	v_mul_f32_e32 v11, v11, v93
	v_mul_f32_e32 v6, v6, v96
	v_mul_f32_e32 v7, v7, v97
	v_mul_f32_e32 v2, v2, v100
	v_mul_f32_e32 v3, v3, v101
	v_mul_f32_e32 v12, v12, v86
	v_mul_f32_e32 v13, v13, v87
	v_mul_f32_e32 v8, v8, v90
	v_mul_f32_e32 v9, v9, v91
	v_mul_f32_e32 v4, v4, v94
	v_mul_f32_e32 v5, v5, v95
	v_mul_f32_e32 v0, v0, v98
	v_mul_f32_e32 v1, v1, v99

; __device__ __forceinline__ float ld_sc1(const float* p) { return __hip_atomic_load(p, __ATOMIC_RELAXED, __HIP_MEMORY_SCOPE_AGENT); }
; __device__ __forceinline__ float quad_row_sum(float s) { s += __shfl_xor(s, 16); s += __shfl_xor(s, 32); return s; }
; __device__ __forceinline__ float dot4(f32x4 v) { return (v[0] * v[0] + v[1] * v[1]) + (v[2] * v[2] + v[3] * v[3]); }
;     __device__ __forceinline__ void operator()(f32x4 (&acc)[2][2][4][2], const Unit& u, int wr, int wc, int fr, int fq) const {
;     ...
;         f32x4 gv[2][2];
; #pragma unroll
;         for (int bj = 0; bj < 2; ++bj) { gv[bj][0] = *(const f32x4*)(g1 + col0 + bj * HALF); gv[bj][1] = *(const f32x4*)(g1 + col0 + bj * HALF + 4); }
; #pragma unroll
;         for (int ai = 0; ai < 2; ++ai)
; #pragma unroll
;             for (int m = 0; m < 4; ++m) { const int row = row0 + ai * HALF + m * 16;
;                 const float r1 = 1.f / sqrtf(ld_sc1(ss1 + row) * (1.f / 2048.f) + 1e-6f);
;                 const float* xrow = (row < 32768 ? xp + (size_t)row * 2048 : xs + (size_t)(row - 32768) * 2048) + col0;
;                 float s = 0.f;
; #pragma unroll
;                 for (int bj = 0; bj < 2; ++bj) { const f32x4 x0 = *(const f32x4*)(xrow + bj * HALF), x1 = *(const f32x4*)(xrow + bj * HALF + 4);
;                     const f32x4 v0 = x0 + acc[ai][bj][m][0] * r1 * gv[bj][0], v1 = x1 + acc[ai][bj][m][1] * r1 * gv[bj][1];
;                     acc[ai][bj][m][0] = v0; acc[ai][bj][m][1] = v1; s += dot4(v0) + dot4(v1); }
;                 s = quad_row_sum(s);
;                 if (fq == 0) __hip_atomic_fetch_add(ss2 + row, s, __ATOMIC_RELAXED, __HIP_MEMORY_SCOPE_AGENT); }
.LBB0_499:
	s_or_b64 exec, exec, s[6:7]
	s_barrier
	global_load_dwordx4 v[116:119], v[154:155], off offset:16
	global_load_dwordx4 v[124:127], v[154:155], off
	s_waitcnt lgkmcnt(0)
	global_load_dwordx4 v[112:115], v[154:155], off offset:528
	global_load_dwordx4 v[120:123], v[154:155], off offset:512
	global_load_dword v192, v[172:173], off sc1
	v_add_u32_e32 v174, 0xffff8000, v166
	v_cmp_gt_i32_e32 vcc, s63, v166
	v_mov_b32_e32 v176, s39
	v_mov_b32_e32 v177, s37
	v_cndmask_b32_e32 v175, 0, v167, vcc
	v_mov_b32_e32 v178, s38
	v_mov_b32_e32 v179, s36
	v_cndmask_b32_e32 v174, v174, v166, vcc
	v_cndmask_b32_e32 v177, v176, v177, vcc
	v_cndmask_b32_e32 v176, v178, v179, vcc
	v_lshlrev_b64 v[174:175], 13, v[174:175]
	v_lshl_add_u64 v[174:175], v[176:177], 0, v[174:175]
	v_lshl_add_u64 v[174:175], v[174:175], 0, v[152:153]
	global_load_dwordx4 v[176:179], v[174:175], off
	global_load_dwordx4 v[180:183], v[174:175], off offset:16
	global_load_dwordx4 v[184:187], v[174:175], off offset:512
	global_load_dwordx4 v[188:191], v[174:175], off offset:528
	s_waitcnt vmcnt(0)
	v_fmamk_f32 v174, v192, 0x3a000000, v220
	v_mul_f32_e32 v175, 0x4f800000, v174
	v_cmp_gt_f32_e32 vcc, s66, v174
	s_nop 1
	v_cndmask_b32_e32 v174, v174, v175, vcc
	v_sqrt_f32_e32 v175, v174
	s_nop 0
	v_add_u32_e32 v192, -1, v175
	v_add_u32_e32 v193, 1, v175
	v_fma_f32 v194, -v192, v175, v174
	v_fma_f32 v195, -v193, v175, v174
	v_cmp_ge_f32_e64 s[6:7], 0, v194
	s_nop 1
	v_cndmask_b32_e64 v175, v175, v192, s[6:7]
	v_cmp_lt_f32_e64 s[6:7], 0, v195
	s_nop 1
	v_cndmask_b32_e64 v175, v175, v193, s[6:7]
	v_mul_f32_e32 v192, 0x37800000, v175
	v_cndmask_b32_e32 v175, v175, v192, vcc
	v_cmp_class_f32_e32 vcc, v174, v221
	s_nop 1
	v_cndmask_b32_e32 v174, v175, v174, vcc
	v_div_scale_f32 v175, s[6:7], v174, v174, 1.0
	v_rcp_f32_e32 v192, v175
	v_div_scale_f32 v193, vcc, 1.0, v174, 1.0
	v_fma_f32 v194, -v175, v192, 1.0
	v_fmac_f32_e32 v192, v194, v192
	v_mul_f32_e32 v194, v193, v192
	v_fma_f32 v195, -v175, v194, v193
	v_fmac_f32_e32 v194, v195, v192
	v_fma_f32 v175, -v175, v194, v193
	v_div_fmas_f32 v175, v175, v192, v194
	v_div_fixup_f32 v174, v175, v174, 1.0
	v_mul_f32_e32 v140, v140, v174
	v_mul_f32_e32 v141, v141, v174
	v_mul_f32_e32 v142, v142, v174
	v_mul_f32_e32 v143, v143, v174
	v_mul_f32_e32 v136, v136, v174
	v_mul_f32_e32 v137, v137, v174
	v_mul_f32_e32 v138, v138, v174
	v_mul_f32_e32 v139, v139, v174
	v_mul_f32_e32 v132, v132, v174
	v_mul_f32_e32 v133, v133, v174
	v_mul_f32_e32 v134, v134, v174
	v_mul_f32_e32 v135, v135, v174
	v_mul_f32_e32 v128, v128, v174
	v_mul_f32_e32 v129, v129, v174
	v_mul_f32_e32 v192, v130, v174
	v_mul_f32_e32 v193, v131, v174
	v_fma_f32 v174, v126, v142, v178
	v_fma_f32 v175, v127, v143, v179
	v_fma_f32 v176, v124, v140, v176
	v_fma_f32 v177, v125, v141, v177
	v_fma_f32 v140, v118, v138, v182
	v_fma_f32 v141, v119, v139, v183
	v_fma_f32 v142, v116, v136, v180
	v_fma_f32 v143, v117, v137, v181
	v_fma_f32 v130, v122, v134, v186
	v_fma_f32 v131, v123, v135, v187
	v_fma_f32 v132, v120, v132, v184
	v_fma_f32 v133, v121, v133, v185
	v_fma_f32 v134, v114, v192, v190
	v_fma_f32 v135, v115, v193, v191
	v_fma_f32 v136, v112, v128, v188
	v_fma_f32 v137, v113, v129, v189
	v_mul_f32_e32 v128, v177, v177
	v_mul_f32_e32 v129, v175, v175
	v_mul_f32_e32 v138, v143, v143
	v_mul_f32_e32 v139, v141, v141
	v_mul_f32_e32 v178, v133, v133
	v_mul_f32_e32 v179, v131, v131
	v_mul_f32_e32 v180, v137, v137
	v_mul_f32_e32 v181, v135, v135
	v_fmac_f32_e32 v128, v176, v176
	v_fmac_f32_e32 v129, v174, v174
	v_fmac_f32_e32 v138, v142, v142
	v_fmac_f32_e32 v139, v140, v140
	v_fmac_f32_e32 v178, v132, v132
	v_fmac_f32_e32 v179, v130, v130
	v_fmac_f32_e32 v180, v136, v136
	v_fmac_f32_e32 v181, v134, v134
	v_add_f32_e32 v128, v128, v129
	v_add_f32_e32 v129, v138, v139
	v_add_f32_e32 v138, v178, v179
	v_add_f32_e32 v139, v180, v181
	v_add_f32_e32 v128, v128, v129
	v_add_f32_e32 v129, v138, v139
	v_add_f32_e32 v128, v128, v129
	ds_bpermute_b32 v129, v222, v128
	s_waitcnt lgkmcnt(0)
	v_add_f32_e32 v138, v128, v129
	ds_bpermute_b32 v139, v223, v138
	v_lshl_add_u64 v[128:129], v[166:167], 2, s[20:21]
	s_and_saveexec_b64 s[6:7], s[0:1]
	s_cbranch_execz .LBB0_501
	s_waitcnt lgkmcnt(0)
	v_add_f32_e32 v138, v138, v139
	global_atomic_add_f32 v[128:129], v138, off
; __device__ __forceinline__ float ld_sc1(const float* p) { return __hip_atomic_load(p, __ATOMIC_RELAXED, __HIP_MEMORY_SCOPE_AGENT); }
; __device__ __forceinline__ float quad_row_sum(float s) { s += __shfl_xor(s, 16); s += __shfl_xor(s, 32); return s; }
; __device__ __forceinline__ float dot4(f32x4 v) { return (v[0] * v[0] + v[1] * v[1]) + (v[2] * v[2] + v[3] * v[3]); }
;     __device__ __forceinline__ void operator()(f32x4 (&acc)[2][2][4][2], const Unit& u, int wr, int wc, int fr, int fq) const {
;     ...
;             for (int m = 0; m < 4; ++m) { const int row = row0 + ai * HALF + m * 16;
;                 const float r1 = 1.f / sqrtf(ld_sc1(ss1 + row) * (1.f / 2048.f) + 1e-6f);
;                 const float* xrow = (row < 32768 ? xp + (size_t)row * 2048 : xs + (size_t)(row - 32768) * 2048) + col0;
;                 float s = 0.f;
; #pragma unroll
;                 for (int bj = 0; bj < 2; ++bj) { const f32x4 x0 = *(const f32x4*)(xrow + bj * HALF), x1 = *(const f32x4*)(xrow + bj * HALF + 4);
;                     const f32x4 v0 = x0 + acc[ai][bj][m][0] * r1 * gv[bj][0], v1 = x1 + acc[ai][bj][m][1] * r1 * gv[bj][1];
;                     acc[ai][bj][m][0] = v0; acc[ai][bj][m][1] = v1; s += dot4(v0) + dot4(v1); }
;                 s = quad_row_sum(s);
;                 if (fq == 0) __hip_atomic_fetch_add(ss2 + row, s, __ATOMIC_RELAXED, __HIP_MEMORY_SCOPE_AGENT); }
.LBB0_501:
	s_or_b64 exec, exec, s[6:7]
	v_or_b32_e32 v138, 16, v166
	s_waitcnt lgkmcnt(0)
	v_ashrrev_i32_e32 v139, 31, v138
	v_lshl_add_u64 v[178:179], v[138:139], 2, s[86:87]
	global_load_dword v194, v[178:179], off sc1
	v_add_u32_e32 v178, 0xffff8010, v166
	v_cmp_gt_i32_e32 vcc, s63, v138
	v_mov_b32_e32 v180, s39
	v_mov_b32_e32 v181, s37
	v_mov_b32_e32 v182, s38
	v_mov_b32_e32 v183, s36
	v_cndmask_b32_e32 v179, 0, v139, vcc
	v_cndmask_b32_e32 v178, v178, v138, vcc
	v_cndmask_b32_e32 v181, v180, v181, vcc
	v_cndmask_b32_e32 v180, v182, v183, vcc
	v_lshlrev_b64 v[178:179], 13, v[178:179]
	v_lshl_add_u64 v[178:179], v[180:181], 0, v[178:179]
	v_lshl_add_u64 v[190:191], v[178:179], 0, v[152:153]
	global_load_dwordx4 v[178:181], v[190:191], off
	global_load_dwordx4 v[182:185], v[190:191], off offset:16
	global_load_dwordx4 v[186:189], v[190:191], off offset:512
	s_nop 0
	global_load_dwordx4 v[190:193], v[190:191], off offset:528
	s_waitcnt vmcnt(4)
	v_fmamk_f32 v194, v194, 0x3a000000, v220
	v_mul_f32_e32 v195, 0x4f800000, v194
	v_cmp_gt_f32_e32 vcc, s66, v194
	s_nop 1
	v_cndmask_b32_e32 v194, v194, v195, vcc
	v_sqrt_f32_e32 v195, v194
	s_nop 0
	v_add_u32_e32 v196, -1, v195
	v_add_u32_e32 v197, 1, v195
	v_fma_f32 v198, -v196, v195, v194
	v_fma_f32 v199, -v197, v195, v194
	v_cmp_ge_f32_e64 s[6:7], 0, v198
	s_nop 1
	v_cndmask_b32_e64 v195, v195, v196, s[6:7]
	v_cmp_lt_f32_e64 s[6:7], 0, v199
	s_nop 1
	v_cndmask_b32_e64 v195, v195, v197, s[6:7]
	v_mul_f32_e32 v196, 0x37800000, v195
	v_cndmask_b32_e32 v195, v195, v196, vcc
	v_cmp_class_f32_e32 vcc, v194, v221
	s_nop 1
	v_cndmask_b32_e32 v194, v195, v194, vcc
	v_div_scale_f32 v195, s[6:7], v194, v194, 1.0
	v_rcp_f32_e32 v196, v195
	v_div_scale_f32 v197, vcc, 1.0, v194, 1.0
	v_fma_f32 v198, -v195, v196, 1.0
	v_fmac_f32_e32 v196, v198, v196
	v_mul_f32_e32 v198, v197, v196
	v_fma_f32 v199, -v195, v198, v197
	v_fmac_f32_e32 v198, v199, v196
	v_fma_f32 v195, -v195, v198, v197
	v_div_fmas_f32 v195, v195, v196, v198
	v_div_fixup_f32 v194, v195, v194, 1.0
	v_mul_f32_e32 v196, v108, v194
	v_mul_f32_e32 v197, v109, v194
	v_mul_f32_e32 v108, v110, v194
	v_mul_f32_e32 v109, v111, v194
	v_mul_f32_e32 v104, v104, v194
	v_mul_f32_e32 v105, v105, v194
	v_mul_f32_e32 v106, v106, v194
	v_mul_f32_e32 v107, v107, v194
	v_mul_f32_e32 v100, v100, v194
	v_mul_f32_e32 v101, v101, v194
	v_mul_f32_e32 v102, v102, v194
	v_mul_f32_e32 v103, v103, v194
	v_mul_f32_e32 v96, v96, v194
	v_mul_f32_e32 v97, v97, v194
	v_mul_f32_e32 v195, v99, v194
	v_mul_f32_e32 v194, v98, v194
	s_waitcnt vmcnt(3)
	v_fma_f32 v108, v126, v108, v180
	v_fma_f32 v109, v127, v109, v181
	v_fma_f32 v178, v124, v196, v178
	v_fma_f32 v179, v125, v197, v179
	s_waitcnt vmcnt(2)
	v_fma_f32 v106, v118, v106, v184
	v_fma_f32 v107, v119, v107, v185
	v_fma_f32 v110, v116, v104, v182
	v_fma_f32 v111, v117, v105, v183
	s_waitcnt vmcnt(1)
	v_fma_f32 v98, v122, v102, v188
	v_fma_f32 v99, v123, v103, v189
	v_fma_f32 v102, v120, v100, v186
	v_fma_f32 v103, v121, v101, v187
	s_waitcnt vmcnt(0)
	v_fma_f32 v100, v114, v194, v192
	v_fma_f32 v101, v115, v195, v193
	v_fma_f32 v104, v112, v96, v190
	v_fma_f32 v105, v113, v97, v191
	v_mul_f32_e32 v96, v179, v179
	v_mul_f32_e32 v97, v109, v109
	v_mul_f32_e32 v180, v111, v111
	v_mul_f32_e32 v181, v107, v107
	v_mul_f32_e32 v182, v103, v103
	v_mul_f32_e32 v183, v99, v99
	v_mul_f32_e32 v184, v105, v105
	v_mul_f32_e32 v185, v101, v101
	v_fmac_f32_e32 v96, v178, v178
	v_fmac_f32_e32 v97, v108, v108
	v_fmac_f32_e32 v180, v110, v110
	v_fmac_f32_e32 v181, v106, v106
	v_fmac_f32_e32 v182, v102, v102
	v_fmac_f32_e32 v183, v98, v98
	v_fmac_f32_e32 v184, v104, v104
	v_fmac_f32_e32 v185, v100, v100
	v_add_f32_e32 v96, v96, v97
	v_add_f32_e32 v97, v180, v181
	v_add_f32_e32 v180, v182, v183
	v_add_f32_e32 v181, v184, v185
	v_add_f32_e32 v96, v96, v97
	v_add_f32_e32 v97, v180, v181
	v_add_f32_e32 v96, v96, v97
	ds_bpermute_b32 v97, v222, v96
	v_lshl_add_u64 v[194:195], v[138:139], 2, s[20:21]
	s_waitcnt lgkmcnt(0)
	v_add_f32_e32 v96, v96, v97
	ds_bpermute_b32 v97, v223, v96
	s_and_saveexec_b64 s[6:7], s[0:1]
	s_cbranch_execz .LBB0_503
	s_waitcnt lgkmcnt(0)
	v_add_f32_e32 v96, v96, v97
	global_atomic_add_f32 v[194:195], v96, off
.LBB0_503:
	s_or_b64 exec, exec, s[6:7]
	v_or_b32_e32 v96, 32, v166
	s_waitcnt lgkmcnt(0)
	v_ashrrev_i32_e32 v97, 31, v96
	v_lshl_add_u64 v[180:181], v[96:97], 2, s[86:87]
	global_load_dword v200, v[180:181], off sc1
	v_add_u32_e32 v180, 0xffff8020, v166
	v_cmp_gt_i32_e32 vcc, s63, v96
	v_mov_b32_e32 v182, s39
	v_mov_b32_e32 v183, s37
	v_mov_b32_e32 v184, s38
	v_mov_b32_e32 v185, s36
	v_cndmask_b32_e32 v181, 0, v97, vcc
	v_cndmask_b32_e32 v180, v180, v96, vcc
	v_cndmask_b32_e32 v183, v182, v183, vcc
	v_cndmask_b32_e32 v182, v184, v185, vcc
	v_lshlrev_b64 v[180:181], 13, v[180:181]
	v_lshl_add_u64 v[180:181], v[182:183], 0, v[180:181]
	v_lshl_add_u64 v[192:193], v[180:181], 0, v[152:153]
	global_load_dwordx4 v[180:183], v[192:193], off
	global_load_dwordx4 v[184:187], v[192:193], off offset:16
	global_load_dwordx4 v[188:191], v[192:193], off offset:512
	global_load_dwordx4 v[196:199], v[192:193], off offset:528
	v_lshl_add_u64 v[204:205], v[96:97], 2, s[20:21]
	s_waitcnt vmcnt(4)
; __device__ __forceinline__ float ld_sc1(const float* p) { return __hip_atomic_load(p, __ATOMIC_RELAXED, __HIP_MEMORY_SCOPE_AGENT); }
; __device__ __forceinline__ float quad_row_sum(float s) { s += __shfl_xor(s, 16); s += __shfl_xor(s, 32); return s; }
; __device__ __forceinline__ float dot4(f32x4 v) { return (v[0] * v[0] + v[1] * v[1]) + (v[2] * v[2] + v[3] * v[3]); }
;     __device__ __forceinline__ void operator()(f32x4 (&acc)[2][2][4][2], const Unit& u, int wr, int wc, int fr, int fq) const {
;     ...
;             for (int m = 0; m < 4; ++m) { const int row = row0 + ai * HALF + m * 16;
;                 const float r1 = 1.f / sqrtf(ld_sc1(ss1 + row) * (1.f / 2048.f) + 1e-6f);
;                 const float* xrow = (row < 32768 ? xp + (size_t)row * 2048 : xs + (size_t)(row - 32768) * 2048) + col0;
;                 float s = 0.f;
; #pragma unroll
;                 for (int bj = 0; bj < 2; ++bj) { const f32x4 x0 = *(const f32x4*)(xrow + bj * HALF), x1 = *(const f32x4*)(xrow + bj * HALF + 4);
;                     const f32x4 v0 = x0 + acc[ai][bj][m][0] * r1 * gv[bj][0], v1 = x1 + acc[ai][bj][m][1] * r1 * gv[bj][1];
;                     acc[ai][bj][m][0] = v0; acc[ai][bj][m][1] = v1; s += dot4(v0) + dot4(v1); }
;                 s = quad_row_sum(s);
;                 if (fq == 0) __hip_atomic_fetch_add(ss2 + row, s, __ATOMIC_RELAXED, __HIP_MEMORY_SCOPE_AGENT); }
	v_fmamk_f32 v192, v200, 0x3a000000, v220
	v_mul_f32_e32 v193, 0x4f800000, v192
	v_cmp_gt_f32_e32 vcc, s66, v192
	s_nop 1
	v_cndmask_b32_e32 v192, v192, v193, vcc
	v_sqrt_f32_e32 v193, v192
	s_nop 0
	v_add_u32_e32 v200, -1, v193
	v_add_u32_e32 v201, 1, v193
	v_fma_f32 v202, -v200, v193, v192
	v_fma_f32 v203, -v201, v193, v192
	v_cmp_ge_f32_e64 s[6:7], 0, v202
	s_nop 1
	v_cndmask_b32_e64 v193, v193, v200, s[6:7]
	v_cmp_lt_f32_e64 s[6:7], 0, v203
	s_nop 1
	v_cndmask_b32_e64 v193, v193, v201, s[6:7]
	v_mul_f32_e32 v200, 0x37800000, v193
	v_cndmask_b32_e32 v193, v193, v200, vcc
	v_cmp_class_f32_e32 vcc, v192, v221
	s_nop 1
	v_cndmask_b32_e32 v192, v193, v192, vcc
	v_div_scale_f32 v193, s[6:7], v192, v192, 1.0
	v_rcp_f32_e32 v200, v193
	v_div_scale_f32 v201, vcc, 1.0, v192, 1.0
	v_fma_f32 v202, -v193, v200, 1.0
	v_fmac_f32_e32 v200, v202, v200
	v_mul_f32_e32 v202, v201, v200
	v_fma_f32 v203, -v193, v202, v201
	v_fmac_f32_e32 v202, v203, v200
	v_fma_f32 v193, -v193, v202, v201
	v_div_fmas_f32 v193, v193, v200, v202
	v_div_fixup_f32 v192, v193, v192, 1.0
	v_mul_f32_e32 v200, v92, v192
	v_mul_f32_e32 v201, v93, v192
	v_mul_f32_e32 v92, v94, v192
	v_mul_f32_e32 v93, v95, v192
	v_mul_f32_e32 v88, v88, v192
	v_mul_f32_e32 v89, v89, v192
	v_mul_f32_e32 v90, v90, v192
	v_mul_f32_e32 v91, v91, v192
	v_mul_f32_e32 v84, v84, v192
	v_mul_f32_e32 v85, v85, v192
	v_mul_f32_e32 v86, v86, v192
	v_mul_f32_e32 v87, v87, v192
	v_mul_f32_e32 v80, v80, v192
	v_mul_f32_e32 v81, v81, v192
	v_mul_f32_e32 v193, v83, v192
	v_mul_f32_e32 v192, v82, v192
	s_waitcnt vmcnt(3)
	v_fma_f32 v92, v126, v92, v182
	v_fma_f32 v93, v127, v93, v183
	v_fma_f32 v180, v124, v200, v180
	v_fma_f32 v181, v125, v201, v181
	s_waitcnt vmcnt(2)
	v_fma_f32 v90, v118, v90, v186
	v_fma_f32 v91, v119, v91, v187
	v_fma_f32 v94, v116, v88, v184
	v_fma_f32 v95, v117, v89, v185
	s_waitcnt vmcnt(1)
	v_fma_f32 v82, v122, v86, v190
	v_fma_f32 v83, v123, v87, v191
	v_fma_f32 v84, v120, v84, v188
	v_fma_f32 v85, v121, v85, v189
	s_waitcnt vmcnt(0)
	v_fma_f32 v86, v114, v192, v198
	v_fma_f32 v87, v115, v193, v199
	v_fma_f32 v88, v112, v80, v196
	v_fma_f32 v89, v113, v81, v197
	v_mul_f32_e32 v80, v181, v181
	v_mul_f32_e32 v81, v93, v93
	v_mul_f32_e32 v182, v95, v95
	v_mul_f32_e32 v183, v91, v91
	v_mul_f32_e32 v184, v85, v85
	v_mul_f32_e32 v185, v83, v83
	v_mul_f32_e32 v186, v89, v89
	v_mul_f32_e32 v187, v87, v87
	v_fmac_f32_e32 v80, v180, v180
	v_fmac_f32_e32 v81, v92, v92
	v_fmac_f32_e32 v182, v94, v94
	v_fmac_f32_e32 v183, v90, v90
	v_fmac_f32_e32 v184, v84, v84
	v_fmac_f32_e32 v185, v82, v82
	v_fmac_f32_e32 v186, v88, v88
	v_fmac_f32_e32 v187, v86, v86
	v_add_f32_e32 v80, v80, v81
	v_add_f32_e32 v81, v182, v183
	v_add_f32_e32 v182, v184, v185
	v_add_f32_e32 v183, v186, v187
	v_add_f32_e32 v80, v80, v81
	v_add_f32_e32 v81, v182, v183
	v_add_f32_e32 v80, v80, v81
	ds_bpermute_b32 v81, v222, v80
	s_waitcnt lgkmcnt(0)
	v_add_f32_e32 v80, v80, v81
	ds_bpermute_b32 v81, v223, v80
	s_and_saveexec_b64 s[6:7], s[0:1]
	s_cbranch_execz .LBB0_505
	s_waitcnt lgkmcnt(0)
	v_add_f32_e32 v80, v80, v81
	global_atomic_add_f32 v[204:205], v80, off
.LBB0_505:
	s_or_b64 exec, exec, s[6:7]
	v_or_b32_e32 v80, 48, v166
	s_waitcnt lgkmcnt(0)
	v_ashrrev_i32_e32 v81, 31, v80
	v_lshl_add_u64 v[182:183], v[80:81], 2, s[86:87]
	global_load_dword v200, v[182:183], off sc1
	v_add_u32_e32 v182, 0xffff8030, v166
	v_cmp_gt_i32_e32 vcc, s63, v80
	v_mov_b32_e32 v184, s39
	v_mov_b32_e32 v185, s37
	v_mov_b32_e32 v186, s38
	v_mov_b32_e32 v187, s36
	v_cndmask_b32_e32 v183, 0, v81, vcc
	v_cndmask_b32_e32 v182, v182, v80, vcc
	v_cndmask_b32_e32 v185, v184, v185, vcc
	v_cndmask_b32_e32 v184, v186, v187, vcc
	v_lshlrev_b64 v[182:183], 13, v[182:183]
	v_lshl_add_u64 v[182:183], v[184:185], 0, v[182:183]
	v_lshl_add_u64 v[196:197], v[182:183], 0, v[152:153]
	global_load_dwordx4 v[182:185], v[196:197], off
	global_load_dwordx4 v[186:189], v[196:197], off offset:16
	global_load_dwordx4 v[190:193], v[196:197], off offset:512
	s_nop 0
	global_load_dwordx4 v[196:199], v[196:197], off offset:528
	s_waitcnt vmcnt(4)
	v_fmamk_f32 v200, v200, 0x3a000000, v220
	v_mul_f32_e32 v201, 0x4f800000, v200
	v_cmp_gt_f32_e32 vcc, s66, v200
	s_nop 1
	v_cndmask_b32_e32 v200, v200, v201, vcc
	v_sqrt_f32_e32 v201, v200
	s_nop 0
	v_add_u32_e32 v202, -1, v201
	v_add_u32_e32 v203, 1, v201
	v_fma_f32 v206, -v202, v201, v200
	v_fma_f32 v207, -v203, v201, v200
	v_cmp_ge_f32_e64 s[6:7], 0, v206
	s_nop 1
	v_cndmask_b32_e64 v201, v201, v202, s[6:7]
	v_cmp_lt_f32_e64 s[6:7], 0, v207
	s_nop 1
	v_cndmask_b32_e64 v201, v201, v203, s[6:7]
	v_mul_f32_e32 v202, 0x37800000, v201
	v_cndmask_b32_e32 v201, v201, v202, vcc
	v_cmp_class_f32_e32 vcc, v200, v221
	s_nop 1
	v_cndmask_b32_e32 v200, v201, v200, vcc
	v_div_scale_f32 v201, s[6:7], v200, v200, 1.0
	v_rcp_f32_e32 v202, v201
	v_div_scale_f32 v203, vcc, 1.0, v200, 1.0
	v_fma_f32 v206, -v201, v202, 1.0
	v_fmac_f32_e32 v202, v206, v202
	v_mul_f32_e32 v206, v203, v202
	v_fma_f32 v207, -v201, v206, v203
	v_fmac_f32_e32 v206, v207, v202
	v_fma_f32 v201, -v201, v206, v203
	v_div_fmas_f32 v201, v201, v202, v206
	v_div_fixup_f32 v200, v201, v200, 1.0
	v_mul_f32_e32 v202, v76, v200
	v_mul_f32_e32 v203, v77, v200
	v_mul_f32_e32 v76, v78, v200
	v_mul_f32_e32 v77, v79, v200
	v_mul_f32_e32 v72, v72, v200
	v_mul_f32_e32 v73, v73, v200
	v_mul_f32_e32 v74, v74, v200
	v_mul_f32_e32 v75, v75, v200
	v_mul_f32_e32 v68, v68, v200
	v_mul_f32_e32 v69, v69, v200
	v_mul_f32_e32 v70, v70, v200
	v_mul_f32_e32 v71, v71, v200
	v_mul_f32_e32 v206, v64, v200
	v_mul_f32_e32 v207, v65, v200
	v_mul_f32_e32 v66, v66, v200
	v_mul_f32_e32 v67, v67, v200
	s_waitcnt vmcnt(3)
; __device__ __forceinline__ float ld_sc1(const float* p) { return __hip_atomic_load(p, __ATOMIC_RELAXED, __HIP_MEMORY_SCOPE_AGENT); }
; __device__ __forceinline__ float quad_row_sum(float s) { s += __shfl_xor(s, 16); s += __shfl_xor(s, 32); return s; }
; __device__ __forceinline__ float dot4(f32x4 v) { return (v[0] * v[0] + v[1] * v[1]) + (v[2] * v[2] + v[3] * v[3]); }
;     __device__ __forceinline__ void operator()(f32x4 (&acc)[2][2][4][2], const Unit& u, int wr, int wc, int fr, int fq) const {
;     ...
;             for (int m = 0; m < 4; ++m) { const int row = row0 + ai * HALF + m * 16;
;                 const float r1 = 1.f / sqrtf(ld_sc1(ss1 + row) * (1.f / 2048.f) + 1e-6f);
;                 const float* xrow = (row < 32768 ? xp + (size_t)row * 2048 : xs + (size_t)(row - 32768) * 2048) + col0;
;                 float s = 0.f;
; #pragma unroll
;                 for (int bj = 0; bj < 2; ++bj) { const f32x4 x0 = *(const f32x4*)(xrow + bj * HALF), x1 = *(const f32x4*)(xrow + bj * HALF + 4);
;                     const f32x4 v0 = x0 + acc[ai][bj][m][0] * r1 * gv[bj][0], v1 = x1 + acc[ai][bj][m][1] * r1 * gv[bj][1];
;                     acc[ai][bj][m][0] = v0; acc[ai][bj][m][1] = v1; s += dot4(v0) + dot4(v1); }
;                 s = quad_row_sum(s);
;                 if (fq == 0) __hip_atomic_fetch_add(ss2 + row, s, __ATOMIC_RELAXED, __HIP_MEMORY_SCOPE_AGENT); }
	v_fma_f32 v76, v126, v76, v184
	v_fma_f32 v77, v127, v77, v185
	v_fma_f32 v182, v124, v202, v182
	v_fma_f32 v183, v125, v203, v183
	s_waitcnt vmcnt(2)
	v_fma_f32 v74, v118, v74, v188
	v_fma_f32 v75, v119, v75, v189
	v_fma_f32 v78, v116, v72, v186
	v_fma_f32 v79, v117, v73, v187
	s_waitcnt vmcnt(1)
	v_fma_f32 v64, v122, v70, v192
	v_fma_f32 v65, v123, v71, v193
	v_fma_f32 v68, v120, v68, v190
	v_fma_f32 v69, v121, v69, v191
	s_waitcnt vmcnt(0)
	v_fma_f32 v66, v114, v66, v198
	v_fma_f32 v67, v115, v67, v199
	v_fma_f32 v72, v112, v206, v196
	v_fma_f32 v73, v113, v207, v197
	v_mul_f32_e32 v70, v183, v183
	v_mul_f32_e32 v71, v77, v77
	v_mul_f32_e32 v184, v79, v79
	v_mul_f32_e32 v185, v75, v75
	v_mul_f32_e32 v186, v69, v69
	v_mul_f32_e32 v187, v65, v65
	v_mul_f32_e32 v188, v73, v73
	v_mul_f32_e32 v189, v67, v67
	v_fmac_f32_e32 v70, v182, v182
	v_fmac_f32_e32 v71, v76, v76
	v_fmac_f32_e32 v184, v78, v78
	v_fmac_f32_e32 v185, v74, v74
	v_fmac_f32_e32 v186, v68, v68
	v_fmac_f32_e32 v187, v64, v64
	v_fmac_f32_e32 v188, v72, v72
	v_fmac_f32_e32 v189, v66, v66
	v_add_f32_e32 v70, v70, v71
	v_add_f32_e32 v71, v184, v185
	v_add_f32_e32 v184, v186, v187
	v_add_f32_e32 v185, v188, v189
	v_add_f32_e32 v70, v70, v71
	v_add_f32_e32 v71, v184, v185
	v_add_f32_e32 v70, v70, v71
	ds_bpermute_b32 v71, v222, v70
	v_lshl_add_u64 v[206:207], v[80:81], 2, s[20:21]
	s_waitcnt lgkmcnt(0)
	v_add_f32_e32 v70, v70, v71
	ds_bpermute_b32 v71, v223, v70
	s_and_saveexec_b64 s[6:7], s[0:1]
	s_cbranch_execz .LBB0_507
	s_waitcnt lgkmcnt(0)
	v_add_f32_e32 v70, v70, v71
	global_atomic_add_f32 v[206:207], v70, off
.LBB0_507:
	s_or_b64 exec, exec, s[6:7]
	global_load_dword v224, v[172:173], off offset:512 sc1
	v_add_u32_e32 v70, 0x80, v166
	v_add_u32_e32 v184, 0xffff8080, v166
	s_waitcnt lgkmcnt(0)
	v_ashrrev_i32_e32 v71, 31, v70
	v_cmp_gt_i32_e32 vcc, s67, v166
	v_mov_b32_e32 v186, s39
	v_mov_b32_e32 v187, s37
	v_mov_b32_e32 v188, s38
	v_mov_b32_e32 v189, s36
	v_cndmask_b32_e32 v185, 0, v71, vcc
	v_cndmask_b32_e32 v184, v184, v70, vcc
	v_cndmask_b32_e32 v187, v186, v187, vcc
	v_cndmask_b32_e32 v186, v188, v189, vcc
	v_lshlrev_b64 v[184:185], 13, v[184:185]
	v_lshl_add_u64 v[184:185], v[186:187], 0, v[184:185]
	v_lshl_add_u64 v[192:193], v[184:185], 0, v[152:153]
	global_load_dwordx4 v[184:187], v[192:193], off
	global_load_dwordx4 v[188:191], v[192:193], off offset:16
	global_load_dwordx4 v[196:199], v[192:193], off offset:512
	global_load_dwordx4 v[200:203], v[192:193], off offset:528
	s_waitcnt vmcnt(4)
	v_fmamk_f32 v192, v224, 0x3a000000, v220
	v_mul_f32_e32 v193, 0x4f800000, v192
	v_cmp_gt_f32_e32 vcc, s66, v192
	s_nop 1
	v_cndmask_b32_e32 v192, v192, v193, vcc
	v_sqrt_f32_e32 v193, v192
	s_nop 0
	v_add_u32_e32 v224, -1, v193
	v_add_u32_e32 v225, 1, v193
	v_fma_f32 v226, -v224, v193, v192
	v_fma_f32 v227, -v225, v193, v192
	v_cmp_ge_f32_e64 s[6:7], 0, v226
	s_nop 1
	v_cndmask_b32_e64 v193, v193, v224, s[6:7]
	v_cmp_lt_f32_e64 s[6:7], 0, v227
	s_nop 1
	v_cndmask_b32_e64 v193, v193, v225, s[6:7]
	v_mul_f32_e32 v224, 0x37800000, v193
	v_cndmask_b32_e32 v193, v193, v224, vcc
	v_cmp_class_f32_e32 vcc, v192, v221
	s_nop 1
	v_cndmask_b32_e32 v192, v193, v192, vcc
	v_div_scale_f32 v193, s[6:7], v192, v192, 1.0
	v_rcp_f32_e32 v224, v193
	v_div_scale_f32 v225, vcc, 1.0, v192, 1.0
	v_fma_f32 v226, -v193, v224, 1.0
	v_fmac_f32_e32 v224, v226, v224
	v_mul_f32_e32 v226, v225, v224
	v_fma_f32 v227, -v193, v226, v225
	v_fmac_f32_e32 v226, v227, v224
	v_fma_f32 v193, -v193, v226, v225
	v_div_fmas_f32 v193, v193, v224, v226
	v_div_fixup_f32 v192, v193, v192, 1.0
	v_mul_f32_e32 v224, v60, v192
	v_mul_f32_e32 v225, v61, v192
	v_mul_f32_e32 v60, v62, v192
	v_mul_f32_e32 v61, v63, v192
	v_mul_f32_e32 v56, v56, v192
	v_mul_f32_e32 v57, v57, v192
	v_mul_f32_e32 v58, v58, v192
	v_mul_f32_e32 v59, v59, v192
	v_mul_f32_e32 v52, v52, v192
	v_mul_f32_e32 v53, v53, v192
	v_mul_f32_e32 v54, v54, v192
	v_mul_f32_e32 v55, v55, v192
	v_mul_f32_e32 v226, v48, v192
	v_mul_f32_e32 v227, v49, v192
	v_mul_f32_e32 v193, v51, v192
	v_mul_f32_e32 v192, v50, v192
	s_waitcnt vmcnt(3)
	v_fma_f32 v60, v126, v60, v186
	v_fma_f32 v61, v127, v61, v187
	v_fma_f32 v184, v124, v224, v184
	v_fma_f32 v185, v125, v225, v185
	s_waitcnt vmcnt(2)
	v_fma_f32 v58, v118, v58, v190
	v_fma_f32 v59, v119, v59, v191
	v_fma_f32 v62, v116, v56, v188
	v_fma_f32 v63, v117, v57, v189
	s_waitcnt vmcnt(1)
	v_fma_f32 v48, v122, v54, v198
	v_fma_f32 v49, v123, v55, v199
	v_fma_f32 v50, v120, v52, v196
	v_fma_f32 v51, v121, v53, v197
	s_waitcnt vmcnt(0)
	v_fma_f32 v52, v114, v192, v202
	v_fma_f32 v53, v115, v193, v203
	v_fma_f32 v56, v112, v226, v200
	v_fma_f32 v57, v113, v227, v201
	v_mul_f32_e32 v54, v185, v185
	v_mul_f32_e32 v55, v61, v61
	v_mul_f32_e32 v186, v63, v63
	v_mul_f32_e32 v187, v59, v59
	v_mul_f32_e32 v188, v51, v51
	v_mul_f32_e32 v189, v49, v49
	v_mul_f32_e32 v190, v57, v57
	v_mul_f32_e32 v191, v53, v53
	v_fmac_f32_e32 v54, v184, v184
	v_fmac_f32_e32 v55, v60, v60
	v_fmac_f32_e32 v186, v62, v62
	v_fmac_f32_e32 v187, v58, v58
	v_fmac_f32_e32 v188, v50, v50
	v_fmac_f32_e32 v189, v48, v48
	v_fmac_f32_e32 v190, v56, v56
	v_fmac_f32_e32 v191, v52, v52
	v_add_f32_e32 v54, v54, v55
	v_add_f32_e32 v55, v186, v187
	v_add_f32_e32 v186, v188, v189
	v_add_f32_e32 v187, v190, v191
	v_add_f32_e32 v54, v54, v55
	v_add_f32_e32 v55, v186, v187
	v_add_f32_e32 v54, v54, v55
	ds_bpermute_b32 v55, v222, v54
	s_waitcnt lgkmcnt(0)
	v_add_f32_e32 v54, v54, v55
	ds_bpermute_b32 v55, v223, v54
	s_and_saveexec_b64 s[6:7], s[0:1]
	s_cbranch_execz .LBB0_509
	v_lshl_add_u64 v[186:187], v[70:71], 2, s[20:21]
	s_waitcnt lgkmcnt(0)
	v_add_f32_e32 v54, v54, v55
	global_atomic_add_f32 v[186:187], v54, off
; __device__ __forceinline__ float ld_sc1(const float* p) { return __hip_atomic_load(p, __ATOMIC_RELAXED, __HIP_MEMORY_SCOPE_AGENT); }
; __device__ __forceinline__ float quad_row_sum(float s) { s += __shfl_xor(s, 16); s += __shfl_xor(s, 32); return s; }
; __device__ __forceinline__ float dot4(f32x4 v) { return (v[0] * v[0] + v[1] * v[1]) + (v[2] * v[2] + v[3] * v[3]); }
;     __device__ __forceinline__ void operator()(f32x4 (&acc)[2][2][4][2], const Unit& u, int wr, int wc, int fr, int fq) const {
;     ...
;             for (int m = 0; m < 4; ++m) { const int row = row0 + ai * HALF + m * 16;
;                 const float r1 = 1.f / sqrtf(ld_sc1(ss1 + row) * (1.f / 2048.f) + 1e-6f);
;                 const float* xrow = (row < 32768 ? xp + (size_t)row * 2048 : xs + (size_t)(row - 32768) * 2048) + col0;
;                 float s = 0.f;
; #pragma unroll
;                 for (int bj = 0; bj < 2; ++bj) { const f32x4 x0 = *(const f32x4*)(xrow + bj * HALF), x1 = *(const f32x4*)(xrow + bj * HALF + 4);
;                     const f32x4 v0 = x0 + acc[ai][bj][m][0] * r1 * gv[bj][0], v1 = x1 + acc[ai][bj][m][1] * r1 * gv[bj][1];
;                     acc[ai][bj][m][0] = v0; acc[ai][bj][m][1] = v1; s += dot4(v0) + dot4(v1); }
;                 s = quad_row_sum(s);
;                 if (fq == 0) __hip_atomic_fetch_add(ss2 + row, s, __ATOMIC_RELAXED, __HIP_MEMORY_SCOPE_AGENT); }
.LBB0_509:
	s_or_b64 exec, exec, s[6:7]
	global_load_dword v192, v[172:173], off offset:576 sc1
	v_add_u32_e32 v54, 0x90, v166
	v_add_u32_e32 v186, 0xffff8090, v166
	s_waitcnt lgkmcnt(0)
	v_ashrrev_i32_e32 v55, 31, v54
	v_cmp_gt_i32_e32 vcc, s68, v166
	v_mov_b32_e32 v188, s39
	v_mov_b32_e32 v189, s37
	v_mov_b32_e32 v190, s38
	v_mov_b32_e32 v191, s36
	v_cndmask_b32_e32 v187, 0, v55, vcc
	v_cndmask_b32_e32 v186, v186, v54, vcc
	v_cndmask_b32_e32 v189, v188, v189, vcc
	v_cndmask_b32_e32 v188, v190, v191, vcc
	v_lshlrev_b64 v[186:187], 13, v[186:187]
	v_lshl_add_u64 v[186:187], v[188:189], 0, v[186:187]
	v_lshl_add_u64 v[190:191], v[186:187], 0, v[152:153]
	global_load_dwordx4 v[186:189], v[190:191], off
	global_load_dwordx4 v[196:199], v[190:191], off offset:16
	global_load_dwordx4 v[200:203], v[190:191], off offset:512
	global_load_dwordx4 v[224:227], v[190:191], off offset:528
	s_waitcnt vmcnt(4)
	v_fmamk_f32 v190, v192, 0x3a000000, v220
	v_mul_f32_e32 v191, 0x4f800000, v190
	v_cmp_gt_f32_e32 vcc, s66, v190
	s_nop 1
	v_cndmask_b32_e32 v190, v190, v191, vcc
	v_sqrt_f32_e32 v191, v190
	s_nop 0
	v_add_u32_e32 v192, -1, v191
	v_add_u32_e32 v193, 1, v191
	v_fma_f32 v228, -v192, v191, v190
	v_fma_f32 v229, -v193, v191, v190
	v_cmp_ge_f32_e64 s[6:7], 0, v228
	s_nop 1
	v_cndmask_b32_e64 v191, v191, v192, s[6:7]
	v_cmp_lt_f32_e64 s[6:7], 0, v229
	s_nop 1
	v_cndmask_b32_e64 v191, v191, v193, s[6:7]
	v_mul_f32_e32 v192, 0x37800000, v191
	v_cndmask_b32_e32 v191, v191, v192, vcc
	v_cmp_class_f32_e32 vcc, v190, v221
	s_nop 1
	v_cndmask_b32_e32 v190, v191, v190, vcc
	v_div_scale_f32 v191, s[6:7], v190, v190, 1.0
	v_rcp_f32_e32 v192, v191
	v_div_scale_f32 v193, vcc, 1.0, v190, 1.0
	v_fma_f32 v228, -v191, v192, 1.0
	v_fmac_f32_e32 v192, v228, v192
	v_mul_f32_e32 v228, v193, v192
	v_fma_f32 v229, -v191, v228, v193
	v_fmac_f32_e32 v228, v229, v192
	v_fma_f32 v191, -v191, v228, v193
	v_div_fmas_f32 v191, v191, v192, v228
	v_div_fixup_f32 v190, v191, v190, 1.0
	v_mul_f32_e32 v44, v44, v190
	v_mul_f32_e32 v45, v45, v190
	v_mul_f32_e32 v46, v46, v190
	v_mul_f32_e32 v47, v47, v190
	v_mul_f32_e32 v40, v40, v190
	v_mul_f32_e32 v41, v41, v190
	v_mul_f32_e32 v42, v42, v190
	v_mul_f32_e32 v43, v43, v190
	v_mul_f32_e32 v36, v36, v190
	v_mul_f32_e32 v37, v37, v190
	v_mul_f32_e32 v38, v38, v190
	v_mul_f32_e32 v39, v39, v190
	v_mul_f32_e32 v228, v32, v190
	v_mul_f32_e32 v229, v33, v190
	v_mul_f32_e32 v34, v34, v190
	v_mul_f32_e32 v35, v35, v190
	s_waitcnt vmcnt(3)
	v_fma_f32 v188, v126, v46, v188
	v_fma_f32 v189, v127, v47, v189
	v_fma_f32 v192, v124, v44, v186
	v_fma_f32 v193, v125, v45, v187
	s_waitcnt vmcnt(2)
	v_fma_f32 v186, v118, v42, v198
	v_fma_f32 v187, v119, v43, v199
	v_fma_f32 v190, v116, v40, v196
	v_fma_f32 v191, v117, v41, v197
	s_waitcnt vmcnt(1)
	v_fma_f32 v32, v122, v38, v202
	v_fma_f32 v33, v123, v39, v203
	v_fma_f32 v36, v120, v36, v200
	v_fma_f32 v37, v121, v37, v201
	s_waitcnt vmcnt(0)
	v_fma_f32 v34, v114, v34, v226
	v_fma_f32 v35, v115, v35, v227
	v_fma_f32 v40, v112, v228, v224
	v_fma_f32 v41, v113, v229, v225
	v_mul_f32_e32 v38, v193, v193
	v_mul_f32_e32 v39, v189, v189
	v_mul_f32_e32 v42, v191, v191
	v_mul_f32_e32 v43, v187, v187
	v_mul_f32_e32 v44, v37, v37
	v_mul_f32_e32 v45, v33, v33
	v_mul_f32_e32 v46, v41, v41
	v_mul_f32_e32 v47, v35, v35
	v_fmac_f32_e32 v38, v192, v192
	v_fmac_f32_e32 v39, v188, v188
	v_fmac_f32_e32 v42, v190, v190
	v_fmac_f32_e32 v43, v186, v186
	v_fmac_f32_e32 v44, v36, v36
	v_fmac_f32_e32 v45, v32, v32
	v_fmac_f32_e32 v46, v40, v40
	v_fmac_f32_e32 v47, v34, v34
	v_add_f32_e32 v38, v38, v39
	v_add_f32_e32 v39, v42, v43
	v_add_f32_e32 v42, v44, v45
	v_add_f32_e32 v43, v46, v47
	v_add_f32_e32 v38, v38, v39
	v_add_f32_e32 v39, v42, v43
	v_add_f32_e32 v38, v38, v39
	ds_bpermute_b32 v39, v222, v38
	s_waitcnt lgkmcnt(0)
	v_add_f32_e32 v38, v38, v39
	ds_bpermute_b32 v39, v223, v38
	s_and_saveexec_b64 s[6:7], s[0:1]
	s_cbranch_execz .LBB0_511
	v_lshl_add_u64 v[42:43], v[54:55], 2, s[20:21]
	s_waitcnt lgkmcnt(0)
	v_add_f32_e32 v38, v38, v39
	global_atomic_add_f32 v[42:43], v38, off
.LBB0_511:
	s_or_b64 exec, exec, s[6:7]
	global_load_dword v196, v[172:173], off offset:640 sc1
	v_add_u32_e32 v38, 0xa0, v166
	v_add_u32_e32 v42, 0xffff80a0, v166
	s_waitcnt lgkmcnt(0)
	v_ashrrev_i32_e32 v39, 31, v38
	v_cmp_gt_i32_e32 vcc, s69, v166
	v_mov_b32_e32 v44, s39
	v_mov_b32_e32 v45, s37
	v_mov_b32_e32 v46, s38
	v_mov_b32_e32 v47, s36
	v_cndmask_b32_e32 v43, 0, v39, vcc
	v_cndmask_b32_e32 v42, v42, v38, vcc
	v_cndmask_b32_e32 v45, v44, v45, vcc
	v_cndmask_b32_e32 v44, v46, v47, vcc
	v_lshlrev_b64 v[42:43], 13, v[42:43]
	v_lshl_add_u64 v[42:43], v[44:45], 0, v[42:43]
	v_lshl_add_u64 v[46:47], v[42:43], 0, v[152:153]
	global_load_dwordx4 v[42:45], v[46:47], off
	global_load_dwordx4 v[224:227], v[46:47], off offset:16
	global_load_dwordx4 v[228:231], v[46:47], off offset:512
	global_load_dwordx4 v[232:235], v[46:47], off offset:528
	s_waitcnt vmcnt(4)
; __device__ __forceinline__ float ld_sc1(const float* p) { return __hip_atomic_load(p, __ATOMIC_RELAXED, __HIP_MEMORY_SCOPE_AGENT); }
; __device__ __forceinline__ float quad_row_sum(float s) { s += __shfl_xor(s, 16); s += __shfl_xor(s, 32); return s; }
; __device__ __forceinline__ float dot4(f32x4 v) { return (v[0] * v[0] + v[1] * v[1]) + (v[2] * v[2] + v[3] * v[3]); }
;     __device__ __forceinline__ void operator()(f32x4 (&acc)[2][2][4][2], const Unit& u, int wr, int wc, int fr, int fq) const {
;     ...
;             for (int m = 0; m < 4; ++m) { const int row = row0 + ai * HALF + m * 16;
;                 const float r1 = 1.f / sqrtf(ld_sc1(ss1 + row) * (1.f / 2048.f) + 1e-6f);
;                 const float* xrow = (row < 32768 ? xp + (size_t)row * 2048 : xs + (size_t)(row - 32768) * 2048) + col0;
;                 float s = 0.f;
; #pragma unroll
;                 for (int bj = 0; bj < 2; ++bj) { const f32x4 x0 = *(const f32x4*)(xrow + bj * HALF), x1 = *(const f32x4*)(xrow + bj * HALF + 4);
;                     const f32x4 v0 = x0 + acc[ai][bj][m][0] * r1 * gv[bj][0], v1 = x1 + acc[ai][bj][m][1] * r1 * gv[bj][1];
;                     acc[ai][bj][m][0] = v0; acc[ai][bj][m][1] = v1; s += dot4(v0) + dot4(v1); }
;                 s = quad_row_sum(s);
;                 if (fq == 0) __hip_atomic_fetch_add(ss2 + row, s, __ATOMIC_RELAXED, __HIP_MEMORY_SCOPE_AGENT); }
	v_fmamk_f32 v46, v196, 0x3a000000, v220
	v_mul_f32_e32 v47, 0x4f800000, v46
	v_cmp_gt_f32_e32 vcc, s66, v46
	s_nop 1
	v_cndmask_b32_e32 v46, v46, v47, vcc
	v_sqrt_f32_e32 v47, v46
	s_nop 0
	v_add_u32_e32 v196, -1, v47
	v_add_u32_e32 v197, 1, v47
	v_fma_f32 v198, -v196, v47, v46
	v_fma_f32 v199, -v197, v47, v46
	v_cmp_ge_f32_e64 s[6:7], 0, v198
	s_nop 1
	v_cndmask_b32_e64 v47, v47, v196, s[6:7]
	v_cmp_lt_f32_e64 s[6:7], 0, v199
	s_nop 1
	v_cndmask_b32_e64 v47, v47, v197, s[6:7]
	v_mul_f32_e32 v196, 0x37800000, v47
	v_cndmask_b32_e32 v47, v47, v196, vcc
	v_cmp_class_f32_e32 vcc, v46, v221
	s_nop 1
	v_cndmask_b32_e32 v46, v47, v46, vcc
	v_div_scale_f32 v47, s[6:7], v46, v46, 1.0
	v_rcp_f32_e32 v196, v47
	v_div_scale_f32 v197, vcc, 1.0, v46, 1.0
	v_fma_f32 v198, -v47, v196, 1.0
	v_fmac_f32_e32 v196, v198, v196
	v_mul_f32_e32 v198, v197, v196
	v_fma_f32 v199, -v47, v198, v197
	v_fmac_f32_e32 v198, v199, v196
	v_fma_f32 v47, -v47, v198, v197
	v_div_fmas_f32 v47, v47, v196, v198
	v_div_fixup_f32 v46, v47, v46, 1.0
	v_mul_f32_e32 v28, v28, v46
	v_mul_f32_e32 v29, v29, v46
	v_mul_f32_e32 v30, v30, v46
	v_mul_f32_e32 v31, v31, v46
	v_mul_f32_e32 v24, v24, v46
	v_mul_f32_e32 v25, v25, v46
	v_mul_f32_e32 v26, v26, v46
	v_mul_f32_e32 v27, v27, v46
	v_mul_f32_e32 v20, v20, v46
	v_mul_f32_e32 v21, v21, v46
	v_mul_f32_e32 v22, v22, v46
	v_mul_f32_e32 v23, v23, v46
	v_mul_f32_e32 v16, v16, v46
	v_mul_f32_e32 v17, v17, v46
	v_mul_f32_e32 v18, v18, v46
	v_mul_f32_e32 v19, v19, v46
	s_waitcnt vmcnt(3)
	v_fma_f32 v198, v126, v30, v44
	v_fma_f32 v199, v127, v31, v45
	v_fma_f32 v202, v124, v28, v42
	v_fma_f32 v203, v125, v29, v43
	s_waitcnt vmcnt(2)
	v_fma_f32 v196, v118, v26, v226
	v_fma_f32 v197, v119, v27, v227
	v_fma_f32 v200, v116, v24, v224
	v_fma_f32 v201, v117, v25, v225
	s_waitcnt vmcnt(1)
	v_fma_f32 v24, v122, v22, v230
	v_fma_f32 v25, v123, v23, v231
	v_fma_f32 v26, v120, v20, v228
	v_fma_f32 v27, v121, v21, v229
	s_waitcnt vmcnt(0)
	v_fma_f32 v28, v114, v18, v234
	v_fma_f32 v29, v115, v19, v235
	v_fma_f32 v42, v112, v16, v232
	v_fma_f32 v43, v113, v17, v233
	v_mul_f32_e32 v16, v203, v203
	v_mul_f32_e32 v17, v199, v199
	v_mul_f32_e32 v18, v201, v201
	v_mul_f32_e32 v19, v197, v197
	v_mul_f32_e32 v20, v27, v27
	v_mul_f32_e32 v21, v25, v25
	v_mul_f32_e32 v22, v43, v43
	v_mul_f32_e32 v23, v29, v29
	v_fmac_f32_e32 v16, v202, v202
	v_fmac_f32_e32 v17, v198, v198
	v_fmac_f32_e32 v18, v200, v200
	v_fmac_f32_e32 v19, v196, v196
	v_fmac_f32_e32 v20, v26, v26
	v_fmac_f32_e32 v21, v24, v24
	v_fmac_f32_e32 v22, v42, v42
	v_fmac_f32_e32 v23, v28, v28
	v_add_f32_e32 v16, v16, v17
	v_add_f32_e32 v17, v18, v19
	v_add_f32_e32 v18, v20, v21
	v_add_f32_e32 v19, v22, v23
	v_add_f32_e32 v16, v16, v17
	v_add_f32_e32 v17, v18, v19
	v_add_f32_e32 v16, v16, v17
	ds_bpermute_b32 v17, v222, v16
	s_waitcnt lgkmcnt(0)
	v_add_f32_e32 v16, v16, v17
	ds_bpermute_b32 v17, v223, v16
	s_and_saveexec_b64 s[6:7], s[0:1]
	s_cbranch_execz .LBB0_513
	v_lshl_add_u64 v[18:19], v[38:39], 2, s[20:21]
	s_waitcnt lgkmcnt(0)
	v_add_f32_e32 v16, v16, v17
	global_atomic_add_f32 v[18:19], v16, off
.LBB0_513:
	s_or_b64 exec, exec, s[6:7]
	global_load_dword v46, v[172:173], off offset:704 sc1
	v_add_u32_e32 v30, 0xb0, v166
	v_add_u32_e32 v16, 0xffff80b0, v166
	v_ashrrev_i32_e32 v31, 31, v30
	v_cmp_gt_i32_e32 vcc, s70, v166
	v_mov_b32_e32 v18, s39
	v_mov_b32_e32 v19, s37
	v_mov_b32_e32 v20, s38
	v_mov_b32_e32 v21, s36
	s_waitcnt lgkmcnt(0)
	v_cndmask_b32_e32 v17, 0, v31, vcc
	v_cndmask_b32_e32 v16, v16, v30, vcc
	v_cndmask_b32_e32 v19, v18, v19, vcc
	v_cndmask_b32_e32 v18, v20, v21, vcc
	v_lshlrev_b64 v[16:17], 13, v[16:17]
	v_lshl_add_u64 v[16:17], v[18:19], 0, v[16:17]
	v_lshl_add_u64 v[44:45], v[16:17], 0, v[152:153]
	global_load_dwordx4 v[16:19], v[44:45], off
	global_load_dwordx4 v[20:23], v[44:45], off offset:16
	global_load_dwordx4 v[224:227], v[44:45], off offset:512
	global_load_dwordx4 v[228:231], v[44:45], off offset:528
	s_waitcnt vmcnt(4)
	v_fmamk_f32 v44, v46, 0x3a000000, v220
	v_mul_f32_e32 v45, 0x4f800000, v44
	v_cmp_gt_f32_e32 vcc, s66, v44
	s_nop 1
	v_cndmask_b32_e32 v44, v44, v45, vcc
	v_sqrt_f32_e32 v45, v44
	s_nop 0
	v_add_u32_e32 v46, -1, v45
	v_add_u32_e32 v47, 1, v45
	v_fma_f32 v172, -v46, v45, v44
	v_fma_f32 v173, -v47, v45, v44
	v_cmp_ge_f32_e64 s[6:7], 0, v172
	s_nop 1
	v_cndmask_b32_e64 v45, v45, v46, s[6:7]
	v_cmp_lt_f32_e64 s[6:7], 0, v173
	s_nop 1
	v_cndmask_b32_e64 v45, v45, v47, s[6:7]
	v_mul_f32_e32 v46, 0x37800000, v45
	v_cndmask_b32_e32 v45, v45, v46, vcc
	v_cmp_class_f32_e32 vcc, v44, v221
	s_nop 1
	v_cndmask_b32_e32 v44, v45, v44, vcc
	v_div_scale_f32 v45, s[6:7], v44, v44, 1.0
	v_rcp_f32_e32 v46, v45
	v_div_scale_f32 v47, vcc, 1.0, v44, 1.0
	v_fma_f32 v172, -v45, v46, 1.0
	v_fmac_f32_e32 v46, v172, v46
	v_mul_f32_e32 v172, v47, v46
	v_fma_f32 v173, -v45, v172, v47
	v_fmac_f32_e32 v172, v173, v46
	v_fma_f32 v45, -v45, v172, v47
	v_div_fmas_f32 v45, v45, v46, v172
	v_div_fixup_f32 v44, v45, v44, 1.0
	v_mul_f32_e32 v12, v12, v44
	v_mul_f32_e32 v13, v13, v44
	v_mul_f32_e32 v14, v14, v44
	v_mul_f32_e32 v15, v15, v44
	v_mul_f32_e32 v8, v8, v44
	v_mul_f32_e32 v9, v9, v44
	v_mul_f32_e32 v10, v10, v44
	v_mul_f32_e32 v11, v11, v44
	v_mul_f32_e32 v4, v4, v44
	v_mul_f32_e32 v5, v5, v44
	v_mul_f32_e32 v6, v6, v44
	v_mul_f32_e32 v7, v7, v44
	v_mul_f32_e32 v0, v0, v44
	v_mul_f32_e32 v1, v1, v44
	v_mul_f32_e32 v2, v2, v44
	v_mul_f32_e32 v3, v3, v44
	s_waitcnt vmcnt(3)
	v_fma_f32 v46, v126, v14, v18
	v_fma_f32 v47, v127, v15, v19
	v_fma_f32 v124, v124, v12, v16
	v_fma_f32 v125, v125, v13, v17
	s_waitcnt vmcnt(2)
	v_fma_f32 v44, v118, v10, v22
	v_fma_f32 v45, v119, v11, v23
	v_fma_f32 v116, v116, v8, v20
	v_fma_f32 v117, v117, v9, v21
	s_waitcnt vmcnt(1)
	v_fma_f32 v16, v122, v6, v226
	v_fma_f32 v17, v123, v7, v227
	v_fma_f32 v20, v120, v4, v224
	v_fma_f32 v21, v121, v5, v225
	s_waitcnt vmcnt(0)
	v_fma_f32 v18, v114, v2, v230
	v_fma_f32 v19, v115, v3, v231
	v_fma_f32 v22, v112, v0, v228
	v_fma_f32 v23, v113, v1, v229
	v_mul_f32_e32 v0, v125, v125
	v_mul_f32_e32 v1, v47, v47
	v_mul_f32_e32 v2, v117, v117
	v_mul_f32_e32 v3, v45, v45
	v_mul_f32_e32 v4, v21, v21
	v_mul_f32_e32 v5, v17, v17
	v_mul_f32_e32 v6, v23, v23
	v_mul_f32_e32 v7, v19, v19
	v_fmac_f32_e32 v0, v124, v124
	v_fmac_f32_e32 v1, v46, v46
	v_fmac_f32_e32 v2, v116, v116
	v_fmac_f32_e32 v3, v44, v44
	v_fmac_f32_e32 v4, v20, v20
	v_fmac_f32_e32 v5, v16, v16
	v_fmac_f32_e32 v6, v22, v22
	v_fmac_f32_e32 v7, v18, v18
	v_add_f32_e32 v0, v0, v1
	v_add_f32_e32 v1, v2, v3
	v_add_f32_e32 v2, v4, v5
	v_add_f32_e32 v3, v6, v7
	v_add_f32_e32 v0, v0, v1
	v_add_f32_e32 v1, v2, v3
	v_add_f32_e32 v0, v0, v1
	ds_bpermute_b32 v1, v222, v0
	s_waitcnt lgkmcnt(0)
	v_add_f32_e32 v0, v0, v1
	ds_bpermute_b32 v1, v223, v0
	s_and_saveexec_b64 s[6:7], s[0:1]
	s_cbranch_execz .LBB0_515
	v_lshl_add_u64 v[2:3], v[30:31], 2, s[20:21]
	s_waitcnt lgkmcnt(0)
	v_add_f32_e32 v0, v0, v1
	global_atomic_add_f32 v[2:3], v0, off

; __device__ __forceinline__ unsigned cvt_pk_bf16(float lo, float hi) { unsigned r; asm volatile("v_cvt_pk_bf16_f32 %0, %1, %2" : "=v"(r) : "v"(lo), "v"(hi)); return r; }
; __device__ __forceinline__ float ld_sc1(const float* p) { return __hip_atomic_load(p, __ATOMIC_RELAXED, __HIP_MEMORY_SCOPE_AGENT); }
;     __device__ __forceinline__ void operator()(f32x4 (&acc)[2][2][4][2], const Unit& u, int wr, int wc, int fr, int fq) const {
;     ...
;         panel_sync(cnt2 + 64 * u.pm);
; #pragma unroll
;         for (int bj = 0; bj < 2; ++bj) { gv[bj][0] = *(const f32x4*)(g2 + col0 + bj * HALF); gv[bj][1] = *(const f32x4*)(g2 + col0 + bj * HALF + 4); }
; #pragma unroll
;         for (int ai = 0; ai < 2; ++ai)
; #pragma unroll
;             for (int m = 0; m < 4; ++m) { const int row = row0 + ai * HALF + m * 16;
;                 const float r2 = 1.f / sqrtf(ld_sc1(ss2 + row) * (1.f / 2048.f) + 1e-6f);
;                 bf16_t* hrow = Hn + (size_t)row * 2048 + col0; bf16_t* orow = X1 + (size_t)row * 2048 + col0;
; #pragma unroll
;                 for (int bj = 0; bj < 2; ++bj) { const f32x4 a0 = acc[ai][bj][m][0], a1 = acc[ai][bj][m][1];
;                     u32x4 wx; wx.x = cvt_pk_bf16(a0[0], a0[1]); wx.y = cvt_pk_bf16(a0[2], a0[3]); wx.z = cvt_pk_bf16(a1[0], a1[1]); wx.w = cvt_pk_bf16(a1[2], a1[3]); *(u32x4*)(orow + bj * HALF) = wx;
;                     const f32x4 v0 = a0 * r2 * gv[bj][0], v1 = a1 * r2 * gv[bj][1];
;                     u32x4 w; w.x = cvt_pk_bf16(v0[0], v0[1]); w.y = cvt_pk_bf16(v0[2], v0[3]); w.z = cvt_pk_bf16(v1[0], v1[1]); w.w = cvt_pk_bf16(v1[2], v1[3]);
;                     *(u32x4*)(hrow + bj * HALF) = w; } }
.LBB0_529:
	s_or_b64 exec, exec, s[6:7]
	s_barrier
	global_load_dwordx4 v[4:7], v[156:157], off offset:16
	global_load_dwordx4 v[12:15], v[156:157], off
	s_waitcnt lgkmcnt(0)
	global_load_dwordx4 v[0:3], v[156:157], off offset:528
	global_load_dwordx4 v[8:11], v[156:157], off offset:512
	global_load_dword v114, v[128:129], off sc1
	v_lshlrev_b64 v[112:113], 12, v[166:167]
	v_lshl_add_u64 v[118:119], v[158:159], 0, v[112:113]
	v_lshl_add_u64 v[120:121], v[160:161], 0, v[112:113]
	v_cvt_pk_bf16_f32 v112, v176, v177
	v_lshlrev_b64 v[96:97], 12, v[96:97]
	v_lshlrev_b64 v[80:81], 12, v[80:81]
	s_cmp_eq_u32 s88, 7
	s_waitcnt vmcnt(0)
	v_fmamk_f32 v113, v114, 0x3a000000, v220
	v_mul_f32_e32 v114, 0x4f800000, v113
	v_cmp_gt_f32_e32 vcc, s66, v113
	s_nop 1
	v_cndmask_b32_e32 v122, v113, v114, vcc
	v_sqrt_f32_e32 v123, v122
	v_cvt_pk_bf16_f32 v113, v174, v175
	v_cvt_pk_bf16_f32 v114, v142, v143
	v_cvt_pk_bf16_f32 v115, v140, v141
	global_store_dwordx4 v[120:121], v[112:115], off
	v_add_u32_e32 v126, -1, v123
	v_add_u32_e32 v127, 1, v123
	v_fma_f32 v166, -v126, v123, v122
	v_fma_f32 v167, -v127, v123, v122
	v_cmp_ge_f32_e64 s[6:7], 0, v166
	s_nop 1
	v_cndmask_b32_e64 v123, v123, v126, s[6:7]
	v_cmp_lt_f32_e64 s[6:7], 0, v167
	s_nop 1
	v_cndmask_b32_e64 v123, v123, v127, s[6:7]
	v_mul_f32_e32 v126, 0x37800000, v123
	v_cndmask_b32_e32 v123, v123, v126, vcc
	v_cmp_class_f32_e32 vcc, v122, v221
	s_nop 1
	v_cndmask_b32_e32 v122, v123, v122, vcc
	v_div_scale_f32 v123, s[6:7], v122, v122, 1.0
	v_rcp_f32_e32 v126, v123
	v_div_scale_f32 v112, vcc, 1.0, v122, 1.0
	v_fma_f32 v113, -v123, v126, 1.0
	v_fmac_f32_e32 v126, v113, v126
	v_mul_f32_e32 v113, v112, v126
	v_fma_f32 v114, -v123, v113, v112
	v_fmac_f32_e32 v113, v114, v126
	v_fma_f32 v112, -v123, v113, v112
	v_div_fmas_f32 v112, v112, v126, v113
	v_div_fixup_f32 v112, v112, v122, 1.0
	v_mul_f32_e32 v114, v176, v112
	v_mul_f32_e32 v115, v177, v112
	v_mul_f32_e32 v122, v174, v112
	v_mul_f32_e32 v123, v175, v112
	v_mul_f32_e32 v126, v142, v112
	v_mul_f32_e32 v127, v143, v112
	v_mul_f32_e32 v140, v140, v112
	v_mul_f32_e32 v141, v141, v112
	v_mul_f32_e32 v142, v132, v112
	v_mul_f32_e32 v143, v133, v112
	v_mul_f32_e32 v166, v130, v112
	v_mul_f32_e32 v167, v131, v112
	v_mul_f32_e32 v172, v136, v112
	v_mul_f32_e32 v173, v137, v112
	v_mul_f32_e32 v113, v135, v112
	v_mul_f32_e32 v112, v134, v112
	v_mul_f32_e32 v114, v12, v114
	v_mul_f32_e32 v115, v13, v115
	v_mul_f32_e32 v122, v14, v122
	v_mul_f32_e32 v123, v15, v123
	v_mul_f32_e32 v140, v6, v140
	v_mul_f32_e32 v141, v7, v141
	v_mul_f32_e32 v126, v4, v126
	v_mul_f32_e32 v127, v5, v127
	v_mul_f32_e32 v174, v2, v112
	v_mul_f32_e32 v175, v3, v113
	v_cvt_pk_bf16_f32 v112, v114, v115
	v_cvt_pk_bf16_f32 v113, v122, v123
	v_cvt_pk_bf16_f32 v114, v126, v127
	v_cvt_pk_bf16_f32 v115, v140, v141
	global_store_dwordx4 v[118:119], v[112:115], off
	v_mul_f32_e32 v166, v10, v166
	v_mul_f32_e32 v167, v11, v167
	v_mul_f32_e32 v142, v8, v142
	v_mul_f32_e32 v143, v9, v143
	v_cvt_pk_bf16_f32 v112, v132, v133
	v_cvt_pk_bf16_f32 v113, v130, v131
	v_cvt_pk_bf16_f32 v114, v136, v137
	v_cvt_pk_bf16_f32 v115, v134, v135
	v_mul_f32_e32 v172, v0, v172
	v_mul_f32_e32 v173, v1, v173
	global_store_dwordx4 v[120:121], v[112:115], off offset:256
	s_nop 1
	v_cvt_pk_bf16_f32 v112, v142, v143
	v_cvt_pk_bf16_f32 v113, v166, v167
	v_cvt_pk_bf16_f32 v114, v172, v173
	v_cvt_pk_bf16_f32 v115, v174, v175
	global_store_dwordx4 v[118:119], v[112:115], off offset:256
	global_load_dword v114, v[194:195], off sc1
	s_nop 0
	v_lshlrev_b64 v[112:113], 12, v[138:139]
	v_lshl_add_u64 v[118:119], v[158:159], 0, v[112:113]
	v_lshl_add_u64 v[120:121], v[160:161], 0, v[112:113]
	v_cvt_pk_bf16_f32 v112, v178, v179
	s_waitcnt vmcnt(0)
	v_fmamk_f32 v113, v114, 0x3a000000, v220
	v_mul_f32_e32 v114, 0x4f800000, v113
	v_cmp_gt_f32_e32 vcc, s66, v113
	s_nop 1
	v_cndmask_b32_e32 v122, v113, v114, vcc
	v_sqrt_f32_e32 v123, v122
	v_cvt_pk_bf16_f32 v113, v108, v109
	v_cvt_pk_bf16_f32 v114, v110, v111
	v_cvt_pk_bf16_f32 v115, v106, v107
	global_store_dwordx4 v[120:121], v[112:115], off
	v_add_u32_e32 v126, -1, v123
	v_add_u32_e32 v127, 1, v123
	v_fma_f32 v130, -v126, v123, v122
	v_fma_f32 v131, -v127, v123, v122
	v_cmp_ge_f32_e64 s[6:7], 0, v130
	s_nop 1
	v_cndmask_b32_e64 v123, v123, v126, s[6:7]
	v_cmp_lt_f32_e64 s[6:7], 0, v131
	s_nop 1
	v_cndmask_b32_e64 v123, v123, v127, s[6:7]
	v_mul_f32_e32 v126, 0x37800000, v123
	v_cndmask_b32_e32 v123, v123, v126, vcc
	v_cmp_class_f32_e32 vcc, v122, v221
	s_nop 1
	v_cndmask_b32_e32 v122, v123, v122, vcc
	v_div_scale_f32 v123, s[6:7], v122, v122, 1.0
	v_rcp_f32_e32 v126, v123
	v_div_scale_f32 v112, vcc, 1.0, v122, 1.0
	v_fma_f32 v113, -v123, v126, 1.0
	v_fmac_f32_e32 v126, v113, v126
	v_mul_f32_e32 v113, v112, v126
	v_fma_f32 v114, -v123, v113, v112
	v_fmac_f32_e32 v113, v114, v126
	v_fma_f32 v112, -v123, v113, v112
	v_div_fmas_f32 v112, v112, v126, v113
	v_div_fixup_f32 v112, v112, v122, 1.0
	v_mul_f32_e32 v108, v108, v112
	v_mul_f32_e32 v109, v109, v112
	v_mul_f32_e32 v114, v178, v112
	v_mul_f32_e32 v115, v179, v112
	v_mul_f32_e32 v110, v110, v112
	v_mul_f32_e32 v111, v111, v112
	v_mul_f32_e32 v106, v106, v112
	v_mul_f32_e32 v107, v107, v112
	v_mul_f32_e32 v122, v102, v112
	v_mul_f32_e32 v123, v103, v112
	v_mul_f32_e32 v126, v98, v112
	v_mul_f32_e32 v127, v99, v112
	v_mul_f32_e32 v130, v104, v112
	v_mul_f32_e32 v131, v105, v112
	v_mul_f32_e32 v113, v101, v112
	v_mul_f32_e32 v112, v100, v112
	v_mul_f32_e32 v108, v14, v108
	v_mul_f32_e32 v109, v15, v109
	v_mul_f32_e32 v114, v12, v114
	v_mul_f32_e32 v115, v13, v115
	v_mul_f32_e32 v132, v6, v106
	v_mul_f32_e32 v133, v7, v107
	v_mul_f32_e32 v110, v4, v110
	v_mul_f32_e32 v111, v5, v111
	v_mul_f32_e32 v126, v10, v126
	v_mul_f32_e32 v127, v11, v127
	v_mul_f32_e32 v122, v8, v122
	v_mul_f32_e32 v123, v9, v123
	v_mul_f32_e32 v112, v2, v112
	v_mul_f32_e32 v113, v3, v113
	v_mul_f32_e32 v130, v0, v130
	v_mul_f32_e32 v131, v1, v131
	v_cvt_pk_bf16_f32 v106, v114, v115
	v_cvt_pk_bf16_f32 v107, v108, v109
	v_cvt_pk_bf16_f32 v108, v110, v111
	v_cvt_pk_bf16_f32 v109, v132, v133
	global_store_dwordx4 v[118:119], v[106:109], off
	v_cvt_pk_bf16_f32 v102, v102, v103
	v_cvt_pk_bf16_f32 v103, v98, v99
	v_cvt_pk_bf16_f32 v104, v104, v105
	v_cvt_pk_bf16_f32 v105, v100, v101
	global_store_dwordx4 v[120:121], v[102:105], off offset:256
	v_cvt_pk_bf16_f32 v98, v122, v123
	v_cvt_pk_bf16_f32 v99, v126, v127
	v_cvt_pk_bf16_f32 v100, v130, v131
	v_cvt_pk_bf16_f32 v101, v112, v113
	global_store_dwordx4 v[118:119], v[98:101], off offset:256
	global_load_dword v98, v[204:205], off sc1
	v_lshl_add_u64 v[102:103], v[160:161], 0, v[96:97]
	v_lshl_add_u64 v[100:101], v[158:159], 0, v[96:97]
	v_cvt_pk_bf16_f32 v96, v180, v181
	s_waitcnt vmcnt(0)
; __device__ __forceinline__ unsigned cvt_pk_bf16(float lo, float hi) { unsigned r; asm volatile("v_cvt_pk_bf16_f32 %0, %1, %2" : "=v"(r) : "v"(lo), "v"(hi)); return r; }
; __device__ __forceinline__ float ld_sc1(const float* p) { return __hip_atomic_load(p, __ATOMIC_RELAXED, __HIP_MEMORY_SCOPE_AGENT); }
;     __device__ __forceinline__ void operator()(f32x4 (&acc)[2][2][4][2], const Unit& u, int wr, int wc, int fr, int fq) const {
;     ...
;             for (int m = 0; m < 4; ++m) { const int row = row0 + ai * HALF + m * 16;
;                 const float r2 = 1.f / sqrtf(ld_sc1(ss2 + row) * (1.f / 2048.f) + 1e-6f);
;                 bf16_t* hrow = Hn + (size_t)row * 2048 + col0; bf16_t* orow = X1 + (size_t)row * 2048 + col0;
; #pragma unroll
;                 for (int bj = 0; bj < 2; ++bj) { const f32x4 a0 = acc[ai][bj][m][0], a1 = acc[ai][bj][m][1];
;                     u32x4 wx; wx.x = cvt_pk_bf16(a0[0], a0[1]); wx.y = cvt_pk_bf16(a0[2], a0[3]); wx.z = cvt_pk_bf16(a1[0], a1[1]); wx.w = cvt_pk_bf16(a1[2], a1[3]); *(u32x4*)(orow + bj * HALF) = wx;
;                     const f32x4 v0 = a0 * r2 * gv[bj][0], v1 = a1 * r2 * gv[bj][1];
;                     u32x4 w; w.x = cvt_pk_bf16(v0[0], v0[1]); w.y = cvt_pk_bf16(v0[2], v0[3]); w.z = cvt_pk_bf16(v1[0], v1[1]); w.w = cvt_pk_bf16(v1[2], v1[3]);
;                     *(u32x4*)(hrow + bj * HALF) = w; } }
	v_fmamk_f32 v97, v98, 0x3a000000, v220
	v_mul_f32_e32 v98, 0x4f800000, v97
	v_cmp_gt_f32_e32 vcc, s66, v97
	s_nop 1
	v_cndmask_b32_e32 v104, v97, v98, vcc
	v_sqrt_f32_e32 v105, v104
	v_cvt_pk_bf16_f32 v97, v92, v93
	v_cvt_pk_bf16_f32 v98, v94, v95
	v_cvt_pk_bf16_f32 v99, v90, v91
	global_store_dwordx4 v[102:103], v[96:99], off
	v_add_u32_e32 v106, -1, v105
	v_add_u32_e32 v107, 1, v105
	v_fma_f32 v108, -v106, v105, v104
	v_fma_f32 v109, -v107, v105, v104
	v_cmp_ge_f32_e64 s[6:7], 0, v108
	s_nop 1
	v_cndmask_b32_e64 v105, v105, v106, s[6:7]
	v_cmp_lt_f32_e64 s[6:7], 0, v109
	s_nop 1
	v_cndmask_b32_e64 v105, v105, v107, s[6:7]
	v_mul_f32_e32 v106, 0x37800000, v105
	v_cndmask_b32_e32 v105, v105, v106, vcc
	v_cmp_class_f32_e32 vcc, v104, v221
	s_nop 1
	v_cndmask_b32_e32 v104, v105, v104, vcc
	v_div_scale_f32 v105, s[6:7], v104, v104, 1.0
	v_rcp_f32_e32 v106, v105
	v_div_scale_f32 v96, vcc, 1.0, v104, 1.0
	v_fma_f32 v97, -v105, v106, 1.0
	v_fmac_f32_e32 v106, v97, v106
	v_mul_f32_e32 v97, v96, v106
	v_fma_f32 v98, -v105, v97, v96
	v_fmac_f32_e32 v97, v98, v106
	v_fma_f32 v96, -v105, v97, v96
	v_div_fmas_f32 v96, v96, v106, v97
	v_div_fixup_f32 v96, v96, v104, 1.0
	v_mul_f32_e32 v92, v92, v96
	v_mul_f32_e32 v93, v93, v96
	v_mul_f32_e32 v98, v180, v96
	v_mul_f32_e32 v99, v181, v96
	v_mul_f32_e32 v94, v94, v96
	v_mul_f32_e32 v95, v95, v96
	v_mul_f32_e32 v90, v90, v96
	v_mul_f32_e32 v91, v91, v96
	v_mul_f32_e32 v92, v14, v92
	v_mul_f32_e32 v93, v15, v93
	v_mul_f32_e32 v104, v84, v96
	v_mul_f32_e32 v105, v85, v96
	v_mul_f32_e32 v106, v82, v96
	v_mul_f32_e32 v107, v83, v96
	v_mul_f32_e32 v108, v88, v96
	v_mul_f32_e32 v109, v89, v96
	v_mul_f32_e32 v97, v87, v96
	v_mul_f32_e32 v96, v86, v96
	v_mul_f32_e32 v98, v12, v98
	v_mul_f32_e32 v99, v13, v99
	v_mul_f32_e32 v110, v6, v90
	v_mul_f32_e32 v111, v7, v91
	v_mul_f32_e32 v94, v4, v94
	v_mul_f32_e32 v95, v5, v95
	v_cvt_pk_bf16_f32 v90, v98, v99
	v_cvt_pk_bf16_f32 v91, v92, v93
	v_mul_f32_e32 v106, v10, v106
	v_mul_f32_e32 v107, v11, v107
	v_cvt_pk_bf16_f32 v92, v94, v95
	v_cvt_pk_bf16_f32 v93, v110, v111
	v_mul_f32_e32 v104, v8, v104
	v_mul_f32_e32 v105, v9, v105
	v_mul_f32_e32 v96, v2, v96
	v_mul_f32_e32 v97, v3, v97
	v_mul_f32_e32 v108, v0, v108
	v_mul_f32_e32 v109, v1, v109
	global_store_dwordx4 v[100:101], v[90:93], off
	s_nop 1
	v_cvt_pk_bf16_f32 v90, v84, v85
	v_cvt_pk_bf16_f32 v91, v82, v83
	v_cvt_pk_bf16_f32 v92, v88, v89
	v_cvt_pk_bf16_f32 v93, v86, v87
	global_store_dwordx4 v[102:103], v[90:93], off offset:256
	v_cvt_pk_bf16_f32 v82, v104, v105
	v_cvt_pk_bf16_f32 v83, v106, v107
	v_cvt_pk_bf16_f32 v84, v108, v109
	v_cvt_pk_bf16_f32 v85, v96, v97
	global_store_dwordx4 v[100:101], v[82:85], off offset:256
	global_load_dword v82, v[206:207], off sc1
	v_lshl_add_u64 v[86:87], v[160:161], 0, v[80:81]
	v_lshl_add_u64 v[84:85], v[158:159], 0, v[80:81]
	v_cvt_pk_bf16_f32 v80, v182, v183
	s_waitcnt vmcnt(0)
	v_fmamk_f32 v81, v82, 0x3a000000, v220
	v_mul_f32_e32 v82, 0x4f800000, v81
	v_cmp_gt_f32_e32 vcc, s66, v81
	s_nop 1
	v_cndmask_b32_e32 v88, v81, v82, vcc
	v_sqrt_f32_e32 v89, v88
	v_cvt_pk_bf16_f32 v81, v76, v77
	v_cvt_pk_bf16_f32 v82, v78, v79
	v_cvt_pk_bf16_f32 v83, v74, v75
	global_store_dwordx4 v[86:87], v[80:83], off
	v_add_u32_e32 v90, -1, v89
	v_add_u32_e32 v91, 1, v89
	v_fma_f32 v92, -v90, v89, v88
	v_fma_f32 v93, -v91, v89, v88
	v_cmp_ge_f32_e64 s[6:7], 0, v92
	s_nop 1
	v_cndmask_b32_e64 v89, v89, v90, s[6:7]
	v_cmp_lt_f32_e64 s[6:7], 0, v93
	s_nop 1
	v_cndmask_b32_e64 v89, v89, v91, s[6:7]
	v_mul_f32_e32 v90, 0x37800000, v89
	v_cndmask_b32_e32 v89, v89, v90, vcc
	v_cmp_class_f32_e32 vcc, v88, v221
	s_nop 1
	v_cndmask_b32_e32 v88, v89, v88, vcc
	v_div_scale_f32 v89, s[6:7], v88, v88, 1.0
	v_rcp_f32_e32 v90, v89
	v_div_scale_f32 v80, vcc, 1.0, v88, 1.0
	v_fma_f32 v81, -v89, v90, 1.0
	v_fmac_f32_e32 v90, v81, v90
	v_mul_f32_e32 v81, v80, v90
	v_fma_f32 v82, -v89, v81, v80
	v_fmac_f32_e32 v81, v82, v90
	v_fma_f32 v80, -v89, v81, v80
	v_div_fmas_f32 v80, v80, v90, v81
	v_div_fixup_f32 v80, v80, v88, 1.0
	v_mul_f32_e32 v76, v76, v80
	v_mul_f32_e32 v77, v77, v80
	v_mul_f32_e32 v82, v182, v80
	v_mul_f32_e32 v83, v183, v80
	v_mul_f32_e32 v78, v78, v80
	v_mul_f32_e32 v79, v79, v80
	v_mul_f32_e32 v74, v74, v80
	v_mul_f32_e32 v75, v75, v80
	v_mul_f32_e32 v76, v14, v76
	v_mul_f32_e32 v77, v15, v77
	v_mul_f32_e32 v88, v68, v80
	v_mul_f32_e32 v89, v69, v80
	v_mul_f32_e32 v90, v64, v80
	v_mul_f32_e32 v91, v65, v80
	v_mul_f32_e32 v92, v72, v80
	v_mul_f32_e32 v93, v73, v80
	v_mul_f32_e32 v81, v67, v80
	v_mul_f32_e32 v80, v66, v80
	v_mul_f32_e32 v82, v12, v82
	v_mul_f32_e32 v83, v13, v83
	v_mul_f32_e32 v94, v6, v74
	v_mul_f32_e32 v95, v7, v75
	v_mul_f32_e32 v78, v4, v78
	v_mul_f32_e32 v79, v5, v79
	v_cvt_pk_bf16_f32 v74, v82, v83
	v_cvt_pk_bf16_f32 v75, v76, v77
	v_mul_f32_e32 v90, v10, v90
	v_mul_f32_e32 v91, v11, v91
	v_cvt_pk_bf16_f32 v76, v78, v79
	v_cvt_pk_bf16_f32 v77, v94, v95
	v_mul_f32_e32 v88, v8, v88
	v_mul_f32_e32 v89, v9, v89
	v_mul_f32_e32 v80, v2, v80
	v_mul_f32_e32 v81, v3, v81
	v_mul_f32_e32 v92, v0, v92
	v_mul_f32_e32 v93, v1, v93
	global_store_dwordx4 v[84:85], v[74:77], off
	s_nop 1
	v_cvt_pk_bf16_f32 v74, v68, v69
	v_cvt_pk_bf16_f32 v75, v64, v65
	v_cvt_pk_bf16_f32 v76, v72, v73
	v_cvt_pk_bf16_f32 v77, v66, v67
	global_store_dwordx4 v[86:87], v[74:77], off offset:256
	v_cvt_pk_bf16_f32 v64, v88, v89
	v_cvt_pk_bf16_f32 v65, v90, v91
	v_cvt_pk_bf16_f32 v66, v92, v93
	v_cvt_pk_bf16_f32 v67, v80, v81
	global_store_dwordx4 v[84:85], v[64:67], off offset:256
	global_load_dword v66, v[128:129], off offset:512 sc1
	s_nop 0
	v_lshlrev_b64 v[64:65], 12, v[70:71]
	v_lshl_add_u64 v[68:69], v[158:159], 0, v[64:65]
	v_lshl_add_u64 v[70:71], v[160:161], 0, v[64:65]
	v_cvt_pk_bf16_f32 v64, v184, v185
	s_waitcnt vmcnt(0)
; __device__ __forceinline__ unsigned cvt_pk_bf16(float lo, float hi) { unsigned r; asm volatile("v_cvt_pk_bf16_f32 %0, %1, %2" : "=v"(r) : "v"(lo), "v"(hi)); return r; }
; __device__ __forceinline__ float ld_sc1(const float* p) { return __hip_atomic_load(p, __ATOMIC_RELAXED, __HIP_MEMORY_SCOPE_AGENT); }
;     __device__ __forceinline__ void operator()(f32x4 (&acc)[2][2][4][2], const Unit& u, int wr, int wc, int fr, int fq) const {
;     ...
;             for (int m = 0; m < 4; ++m) { const int row = row0 + ai * HALF + m * 16;
;                 const float r2 = 1.f / sqrtf(ld_sc1(ss2 + row) * (1.f / 2048.f) + 1e-6f);
;                 bf16_t* hrow = Hn + (size_t)row * 2048 + col0; bf16_t* orow = X1 + (size_t)row * 2048 + col0;
; #pragma unroll
;                 for (int bj = 0; bj < 2; ++bj) { const f32x4 a0 = acc[ai][bj][m][0], a1 = acc[ai][bj][m][1];
;                     u32x4 wx; wx.x = cvt_pk_bf16(a0[0], a0[1]); wx.y = cvt_pk_bf16(a0[2], a0[3]); wx.z = cvt_pk_bf16(a1[0], a1[1]); wx.w = cvt_pk_bf16(a1[2], a1[3]); *(u32x4*)(orow + bj * HALF) = wx;
;                     const f32x4 v0 = a0 * r2 * gv[bj][0], v1 = a1 * r2 * gv[bj][1];
;                     u32x4 w; w.x = cvt_pk_bf16(v0[0], v0[1]); w.y = cvt_pk_bf16(v0[2], v0[3]); w.z = cvt_pk_bf16(v1[0], v1[1]); w.w = cvt_pk_bf16(v1[2], v1[3]);
;                     *(u32x4*)(hrow + bj * HALF) = w; } }
	v_fmamk_f32 v65, v66, 0x3a000000, v220
	v_mul_f32_e32 v66, 0x4f800000, v65
	v_cmp_gt_f32_e32 vcc, s66, v65
	s_nop 1
	v_cndmask_b32_e32 v72, v65, v66, vcc
	v_sqrt_f32_e32 v73, v72
	v_cvt_pk_bf16_f32 v65, v60, v61
	v_cvt_pk_bf16_f32 v66, v62, v63
	v_cvt_pk_bf16_f32 v67, v58, v59
	global_store_dwordx4 v[70:71], v[64:67], off
	v_add_u32_e32 v74, -1, v73
	v_add_u32_e32 v75, 1, v73
	v_fma_f32 v76, -v74, v73, v72
	v_fma_f32 v77, -v75, v73, v72
	v_cmp_ge_f32_e64 s[6:7], 0, v76
	s_nop 1
	v_cndmask_b32_e64 v73, v73, v74, s[6:7]
	v_cmp_lt_f32_e64 s[6:7], 0, v77
	s_nop 1
	v_cndmask_b32_e64 v73, v73, v75, s[6:7]
	v_mul_f32_e32 v74, 0x37800000, v73
	v_cndmask_b32_e32 v73, v73, v74, vcc
	v_cmp_class_f32_e32 vcc, v72, v221
	s_nop 1
	v_cndmask_b32_e32 v72, v73, v72, vcc
	v_div_scale_f32 v73, s[6:7], v72, v72, 1.0
	v_rcp_f32_e32 v74, v73
	v_div_scale_f32 v64, vcc, 1.0, v72, 1.0
	v_fma_f32 v65, -v73, v74, 1.0
	v_fmac_f32_e32 v74, v65, v74
	v_mul_f32_e32 v65, v64, v74
	v_fma_f32 v66, -v73, v65, v64
	v_fmac_f32_e32 v65, v66, v74
	v_fma_f32 v64, -v73, v65, v64
	v_div_fmas_f32 v64, v64, v74, v65
	v_div_fixup_f32 v64, v64, v72, 1.0
	v_mul_f32_e32 v60, v60, v64
	v_mul_f32_e32 v61, v61, v64
	v_mul_f32_e32 v66, v184, v64
	v_mul_f32_e32 v67, v185, v64
	v_mul_f32_e32 v62, v62, v64
	v_mul_f32_e32 v63, v63, v64
	v_mul_f32_e32 v58, v58, v64
	v_mul_f32_e32 v59, v59, v64
	v_mul_f32_e32 v60, v14, v60
	v_mul_f32_e32 v61, v15, v61
	v_mul_f32_e32 v72, v50, v64
	v_mul_f32_e32 v73, v51, v64
	v_mul_f32_e32 v74, v48, v64
	v_mul_f32_e32 v75, v49, v64
	v_mul_f32_e32 v76, v56, v64
	v_mul_f32_e32 v77, v57, v64
	v_mul_f32_e32 v65, v53, v64
	v_mul_f32_e32 v64, v52, v64
	v_mul_f32_e32 v66, v12, v66
	v_mul_f32_e32 v67, v13, v67
	v_mul_f32_e32 v78, v6, v58
	v_mul_f32_e32 v79, v7, v59
	v_mul_f32_e32 v62, v4, v62
	v_mul_f32_e32 v63, v5, v63
	v_cvt_pk_bf16_f32 v58, v66, v67
	v_cvt_pk_bf16_f32 v59, v60, v61
	v_mul_f32_e32 v74, v10, v74
	v_mul_f32_e32 v75, v11, v75
	v_cvt_pk_bf16_f32 v60, v62, v63
	v_cvt_pk_bf16_f32 v61, v78, v79
	v_mul_f32_e32 v72, v8, v72
	v_mul_f32_e32 v73, v9, v73
	v_mul_f32_e32 v64, v2, v64
	v_mul_f32_e32 v65, v3, v65
	v_mul_f32_e32 v76, v0, v76
	v_mul_f32_e32 v77, v1, v77
	global_store_dwordx4 v[68:69], v[58:61], off
	s_nop 1
	v_cvt_pk_bf16_f32 v58, v50, v51
	v_cvt_pk_bf16_f32 v59, v48, v49
	v_cvt_pk_bf16_f32 v60, v56, v57
	v_cvt_pk_bf16_f32 v61, v52, v53
	global_store_dwordx4 v[70:71], v[58:61], off offset:256
	v_cvt_pk_bf16_f32 v48, v72, v73
	v_cvt_pk_bf16_f32 v49, v74, v75
	v_cvt_pk_bf16_f32 v50, v76, v77
	v_cvt_pk_bf16_f32 v51, v64, v65
	global_store_dwordx4 v[68:69], v[48:51], off offset:256
	global_load_dword v50, v[128:129], off offset:576 sc1
	s_nop 0
	v_lshlrev_b64 v[48:49], 12, v[54:55]
	v_lshl_add_u64 v[52:53], v[158:159], 0, v[48:49]
	v_lshl_add_u64 v[54:55], v[160:161], 0, v[48:49]
	v_cvt_pk_bf16_f32 v48, v192, v193
	s_waitcnt vmcnt(0)
	v_fmamk_f32 v49, v50, 0x3a000000, v220
	v_mul_f32_e32 v50, 0x4f800000, v49
	v_cmp_gt_f32_e32 vcc, s66, v49
	s_nop 1
	v_cndmask_b32_e32 v56, v49, v50, vcc
	v_sqrt_f32_e32 v57, v56
	v_cvt_pk_bf16_f32 v49, v188, v189
	v_cvt_pk_bf16_f32 v50, v190, v191
	v_cvt_pk_bf16_f32 v51, v186, v187
	global_store_dwordx4 v[54:55], v[48:51], off
	v_add_u32_e32 v58, -1, v57
	v_add_u32_e32 v59, 1, v57
	v_fma_f32 v60, -v58, v57, v56
	v_fma_f32 v61, -v59, v57, v56
	v_cmp_ge_f32_e64 s[6:7], 0, v60
	s_nop 1
	v_cndmask_b32_e64 v57, v57, v58, s[6:7]
	v_cmp_lt_f32_e64 s[6:7], 0, v61
	s_nop 1
	v_cndmask_b32_e64 v57, v57, v59, s[6:7]
	v_mul_f32_e32 v58, 0x37800000, v57
	v_cndmask_b32_e32 v57, v57, v58, vcc
	v_cmp_class_f32_e32 vcc, v56, v221
	s_nop 1
	v_cndmask_b32_e32 v56, v57, v56, vcc
	v_div_scale_f32 v57, s[6:7], v56, v56, 1.0
	v_rcp_f32_e32 v58, v57
	v_div_scale_f32 v48, vcc, 1.0, v56, 1.0
	v_fma_f32 v49, -v57, v58, 1.0
	v_fmac_f32_e32 v58, v49, v58
	v_mul_f32_e32 v49, v48, v58
	v_fma_f32 v50, -v57, v49, v48
	v_fmac_f32_e32 v49, v50, v58
	v_fma_f32 v48, -v57, v49, v48
	v_div_fmas_f32 v48, v48, v58, v49
	v_div_fixup_f32 v48, v48, v56, 1.0
	v_mul_f32_e32 v50, v192, v48
	v_mul_f32_e32 v51, v193, v48
	v_mul_f32_e32 v56, v188, v48
	v_mul_f32_e32 v57, v189, v48
	v_mul_f32_e32 v58, v190, v48
	v_mul_f32_e32 v59, v191, v48
	v_mul_f32_e32 v60, v186, v48
	v_mul_f32_e32 v61, v187, v48
	v_mul_f32_e32 v62, v36, v48
	v_mul_f32_e32 v63, v37, v48
	v_mul_f32_e32 v64, v32, v48
	v_mul_f32_e32 v65, v33, v48
	v_mul_f32_e32 v66, v40, v48
	v_mul_f32_e32 v67, v41, v48
	v_mul_f32_e32 v49, v35, v48
	v_mul_f32_e32 v48, v34, v48
	v_mul_f32_e32 v50, v12, v50
	v_mul_f32_e32 v51, v13, v51
	v_mul_f32_e32 v56, v14, v56
	v_mul_f32_e32 v57, v15, v57
	v_mul_f32_e32 v60, v6, v60
	v_mul_f32_e32 v61, v7, v61
	v_mul_f32_e32 v58, v4, v58
	v_mul_f32_e32 v59, v5, v59
	v_mul_f32_e32 v68, v2, v48
	v_mul_f32_e32 v69, v3, v49
	v_cvt_pk_bf16_f32 v48, v50, v51
	v_cvt_pk_bf16_f32 v49, v56, v57
	v_cvt_pk_bf16_f32 v50, v58, v59
	v_cvt_pk_bf16_f32 v51, v60, v61
	v_mul_f32_e32 v64, v10, v64
	v_mul_f32_e32 v65, v11, v65
	v_mul_f32_e32 v62, v8, v62
	v_mul_f32_e32 v63, v9, v63
	v_mul_f32_e32 v66, v0, v66
	v_mul_f32_e32 v67, v1, v67
	global_store_dwordx4 v[52:53], v[48:51], off
	s_nop 1
	v_cvt_pk_bf16_f32 v48, v36, v37
	v_cvt_pk_bf16_f32 v49, v32, v33
	v_cvt_pk_bf16_f32 v50, v40, v41
	v_cvt_pk_bf16_f32 v51, v34, v35
	global_store_dwordx4 v[54:55], v[48:51], off offset:256
	v_cvt_pk_bf16_f32 v32, v62, v63
	v_cvt_pk_bf16_f32 v33, v64, v65
	v_cvt_pk_bf16_f32 v34, v66, v67
	v_cvt_pk_bf16_f32 v35, v68, v69
	global_store_dwordx4 v[52:53], v[32:35], off offset:256
	global_load_dword v34, v[128:129], off offset:640 sc1
	s_nop 0
	v_lshlrev_b64 v[32:33], 12, v[38:39]
	v_lshl_add_u64 v[36:37], v[158:159], 0, v[32:33]
	v_lshl_add_u64 v[38:39], v[160:161], 0, v[32:33]
	v_cvt_pk_bf16_f32 v32, v202, v203
	s_waitcnt vmcnt(0)
; __device__ __forceinline__ unsigned cvt_pk_bf16(float lo, float hi) { unsigned r; asm volatile("v_cvt_pk_bf16_f32 %0, %1, %2" : "=v"(r) : "v"(lo), "v"(hi)); return r; }
; __device__ __forceinline__ float ld_sc1(const float* p) { return __hip_atomic_load(p, __ATOMIC_RELAXED, __HIP_MEMORY_SCOPE_AGENT); }
;     __device__ __forceinline__ void operator()(f32x4 (&acc)[2][2][4][2], const Unit& u, int wr, int wc, int fr, int fq) const {
;     ...
;             for (int m = 0; m < 4; ++m) { const int row = row0 + ai * HALF + m * 16;
;                 const float r2 = 1.f / sqrtf(ld_sc1(ss2 + row) * (1.f / 2048.f) + 1e-6f);
;                 bf16_t* hrow = Hn + (size_t)row * 2048 + col0; bf16_t* orow = X1 + (size_t)row * 2048 + col0;
; #pragma unroll
;                 for (int bj = 0; bj < 2; ++bj) { const f32x4 a0 = acc[ai][bj][m][0], a1 = acc[ai][bj][m][1];
;                     u32x4 wx; wx.x = cvt_pk_bf16(a0[0], a0[1]); wx.y = cvt_pk_bf16(a0[2], a0[3]); wx.z = cvt_pk_bf16(a1[0], a1[1]); wx.w = cvt_pk_bf16(a1[2], a1[3]); *(u32x4*)(orow + bj * HALF) = wx;
;                     const f32x4 v0 = a0 * r2 * gv[bj][0], v1 = a1 * r2 * gv[bj][1];
;                     u32x4 w; w.x = cvt_pk_bf16(v0[0], v0[1]); w.y = cvt_pk_bf16(v0[2], v0[3]); w.z = cvt_pk_bf16(v1[0], v1[1]); w.w = cvt_pk_bf16(v1[2], v1[3]);
;                     *(u32x4*)(hrow + bj * HALF) = w; } }
	v_fmamk_f32 v33, v34, 0x3a000000, v220
	v_mul_f32_e32 v34, 0x4f800000, v33
	v_cmp_gt_f32_e32 vcc, s66, v33
	s_nop 1
	v_cndmask_b32_e32 v40, v33, v34, vcc
	v_sqrt_f32_e32 v41, v40
	v_cvt_pk_bf16_f32 v33, v198, v199
	v_cvt_pk_bf16_f32 v34, v200, v201
	v_cvt_pk_bf16_f32 v35, v196, v197
	global_store_dwordx4 v[38:39], v[32:35], off
	v_add_u32_e32 v48, -1, v41
	v_add_u32_e32 v49, 1, v41
	v_fma_f32 v50, -v48, v41, v40
	v_fma_f32 v51, -v49, v41, v40
	v_cmp_ge_f32_e64 s[6:7], 0, v50
	s_nop 1
	v_cndmask_b32_e64 v41, v41, v48, s[6:7]
	v_cmp_lt_f32_e64 s[6:7], 0, v51
	s_nop 1
	v_cndmask_b32_e64 v41, v41, v49, s[6:7]
	v_mul_f32_e32 v48, 0x37800000, v41
	v_cndmask_b32_e32 v41, v41, v48, vcc
	v_cmp_class_f32_e32 vcc, v40, v221
	s_nop 1
	v_cndmask_b32_e32 v40, v41, v40, vcc
	v_div_scale_f32 v41, s[6:7], v40, v40, 1.0
	v_rcp_f32_e32 v48, v41
	v_div_scale_f32 v32, vcc, 1.0, v40, 1.0
	v_fma_f32 v33, -v41, v48, 1.0
	v_fmac_f32_e32 v48, v33, v48
	v_mul_f32_e32 v33, v32, v48
	v_fma_f32 v34, -v41, v33, v32
	v_fmac_f32_e32 v33, v34, v48
	v_fma_f32 v32, -v41, v33, v32
	v_div_fmas_f32 v32, v32, v48, v33
	v_div_fixup_f32 v32, v32, v40, 1.0
	v_mul_f32_e32 v34, v202, v32
	v_mul_f32_e32 v35, v203, v32
	v_mul_f32_e32 v40, v198, v32
	v_mul_f32_e32 v41, v199, v32
	v_mul_f32_e32 v48, v200, v32
	v_mul_f32_e32 v49, v201, v32
	v_mul_f32_e32 v50, v196, v32
	v_mul_f32_e32 v51, v197, v32
	v_mul_f32_e32 v52, v26, v32
	v_mul_f32_e32 v53, v27, v32
	v_mul_f32_e32 v54, v24, v32
	v_mul_f32_e32 v55, v25, v32
	v_mul_f32_e32 v56, v42, v32
	v_mul_f32_e32 v57, v43, v32
	v_mul_f32_e32 v33, v29, v32
	v_mul_f32_e32 v32, v28, v32
	v_mul_f32_e32 v34, v12, v34
	v_mul_f32_e32 v35, v13, v35
	v_mul_f32_e32 v40, v14, v40
	v_mul_f32_e32 v41, v15, v41
	v_mul_f32_e32 v50, v6, v50
	v_mul_f32_e32 v51, v7, v51
	v_mul_f32_e32 v48, v4, v48
	v_mul_f32_e32 v49, v5, v49
	v_mul_f32_e32 v58, v2, v32
	v_mul_f32_e32 v59, v3, v33
	v_cvt_pk_bf16_f32 v32, v34, v35
	v_cvt_pk_bf16_f32 v33, v40, v41
	v_cvt_pk_bf16_f32 v34, v48, v49
	v_cvt_pk_bf16_f32 v35, v50, v51
	v_mul_f32_e32 v54, v10, v54
	v_mul_f32_e32 v55, v11, v55
	v_mul_f32_e32 v52, v8, v52
	v_mul_f32_e32 v53, v9, v53
	v_mul_f32_e32 v56, v0, v56
	v_mul_f32_e32 v57, v1, v57
	global_store_dwordx4 v[36:37], v[32:35], off
	s_nop 1
	v_cvt_pk_bf16_f32 v32, v26, v27
	v_cvt_pk_bf16_f32 v33, v24, v25
	v_cvt_pk_bf16_f32 v34, v42, v43
	v_cvt_pk_bf16_f32 v35, v28, v29
	global_store_dwordx4 v[38:39], v[32:35], off offset:256
	v_cvt_pk_bf16_f32 v24, v52, v53
	v_cvt_pk_bf16_f32 v25, v54, v55
	v_cvt_pk_bf16_f32 v26, v56, v57
	v_cvt_pk_bf16_f32 v27, v58, v59
	global_store_dwordx4 v[36:37], v[24:27], off offset:256
	global_load_dword v26, v[128:129], off offset:704 sc1
	s_nop 0
	v_lshlrev_b64 v[24:25], 12, v[30:31]
	v_lshl_add_u64 v[28:29], v[158:159], 0, v[24:25]
	v_lshl_add_u64 v[30:31], v[160:161], 0, v[24:25]
	v_cvt_pk_bf16_f32 v24, v124, v125
	s_waitcnt vmcnt(0)
	v_fmamk_f32 v25, v26, 0x3a000000, v220
	v_mul_f32_e32 v26, 0x4f800000, v25
	v_cmp_gt_f32_e32 vcc, s66, v25
	s_nop 1
	v_cndmask_b32_e32 v32, v25, v26, vcc
	v_sqrt_f32_e32 v33, v32
	v_cvt_pk_bf16_f32 v25, v46, v47
	v_cvt_pk_bf16_f32 v26, v116, v117
	v_cvt_pk_bf16_f32 v27, v44, v45
	global_store_dwordx4 v[30:31], v[24:27], off
	v_add_u32_e32 v34, -1, v33
	v_add_u32_e32 v35, 1, v33
	v_fma_f32 v36, -v34, v33, v32
	v_fma_f32 v37, -v35, v33, v32
	v_cmp_ge_f32_e64 s[6:7], 0, v36
	s_nop 1
	v_cndmask_b32_e64 v33, v33, v34, s[6:7]
	v_cmp_lt_f32_e64 s[6:7], 0, v37
	s_nop 1
	v_cndmask_b32_e64 v33, v33, v35, s[6:7]
	v_mul_f32_e32 v34, 0x37800000, v33
	v_cndmask_b32_e32 v33, v33, v34, vcc
	v_cmp_class_f32_e32 vcc, v32, v221
	s_nop 1
	v_cndmask_b32_e32 v32, v33, v32, vcc
	v_div_scale_f32 v33, s[6:7], v32, v32, 1.0
	v_rcp_f32_e32 v34, v33
	v_div_scale_f32 v24, vcc, 1.0, v32, 1.0
	s_mov_b64 s[6:7], -1
	v_fma_f32 v25, -v33, v34, 1.0
	v_fmac_f32_e32 v34, v25, v34
	v_mul_f32_e32 v25, v24, v34
	v_fma_f32 v26, -v33, v25, v24
	v_fmac_f32_e32 v25, v26, v34
	v_fma_f32 v24, -v33, v25, v24
	v_div_fmas_f32 v24, v24, v34, v25
	v_div_fixup_f32 v24, v24, v32, 1.0
	v_mul_f32_e32 v26, v124, v24
	v_mul_f32_e32 v27, v125, v24
	v_mul_f32_e32 v32, v46, v24
	v_mul_f32_e32 v33, v47, v24
	v_mul_f32_e32 v34, v116, v24
	v_mul_f32_e32 v35, v117, v24
	v_mul_f32_e32 v36, v44, v24
	v_mul_f32_e32 v37, v45, v24
	v_mul_f32_e32 v38, v20, v24
	v_mul_f32_e32 v39, v21, v24
	v_mul_f32_e32 v40, v16, v24
	v_mul_f32_e32 v41, v17, v24
	v_mul_f32_e32 v42, v22, v24
	v_mul_f32_e32 v43, v23, v24
	v_mul_f32_e32 v25, v19, v24
	v_mul_f32_e32 v24, v18, v24
	v_mul_f32_e32 v14, v14, v32
	v_mul_f32_e32 v15, v15, v33
	v_mul_f32_e32 v12, v12, v26
	v_mul_f32_e32 v13, v13, v27
	v_mul_f32_e32 v6, v6, v36
	v_mul_f32_e32 v7, v7, v37
	v_mul_f32_e32 v4, v4, v34
	v_mul_f32_e32 v5, v5, v35
	v_mul_f32_e32 v24, v2, v24
	v_mul_f32_e32 v25, v3, v25
	v_mul_f32_e32 v26, v0, v42
	v_mul_f32_e32 v27, v1, v43
	v_cvt_pk_bf16_f32 v0, v12, v13
	v_cvt_pk_bf16_f32 v1, v14, v15
	v_cvt_pk_bf16_f32 v2, v4, v5
	v_cvt_pk_bf16_f32 v3, v6, v7
	global_store_dwordx4 v[28:29], v[0:3], off
	v_mul_f32_e32 v10, v10, v40
	v_mul_f32_e32 v11, v11, v41
	v_mul_f32_e32 v8, v8, v38
	v_mul_f32_e32 v9, v9, v39
	v_cvt_pk_bf16_f32 v0, v20, v21
	v_cvt_pk_bf16_f32 v1, v16, v17
	v_cvt_pk_bf16_f32 v2, v22, v23
	v_cvt_pk_bf16_f32 v3, v18, v19
	global_store_dwordx4 v[30:31], v[0:3], off offset:256
	s_nop 1
	v_cvt_pk_bf16_f32 v0, v8, v9
	v_cvt_pk_bf16_f32 v1, v10, v11
	v_cvt_pk_bf16_f32 v2, v26, v27
	v_cvt_pk_bf16_f32 v3, v24, v25
	global_store_dwordx4 v[28:29], v[0:3], off offset:256
	s_cbranch_scc1 .LBB0_464
	s_andn2_b64 vcc, exec, s[18:19]
	s_cbranch_vccnz .LBB0_463
	s_barrier
	s_branch .LBB0_463

; __device__ __forceinline__ float ld_sc1(const float* p) { return __hip_atomic_load(p, __ATOMIC_RELAXED, __HIP_MEMORY_SCOPE_AGENT); }
;     __device__ __forceinline__ void operator()(f32x4 (&acc)[2][2][4][2], const Unit& u, int wr, int wc, int fr, int fq) const {
;     ...
;         panel_sync(cnt + 64 * u.pm);
;         f32x4 gv[2][2];
; #pragma unroll
;         for (int bj = 0; bj < 2; ++bj) { gv[bj][0] = *(const f32x4*)(g + col0 + bj * HALF); gv[bj][1] = *(const f32x4*)(g + col0 + bj * HALF + 4); }
; #pragma unroll
;         for (int ai = 0; ai < 2; ++ai)
; #pragma unroll
;             for (int m = 0; m < 4; ++m) { const int row = row0 + ai * HALF + m * 16;
;                 const float r1 = 1.f / sqrtf(ld_sc1(ss + row) * (1.f / 2048.f) + 1e-6f);
;                 float* orow = OUT + (size_t)row * 2048 + col0;
; #pragma unroll
;                 for (int bj = 0; bj < 2; ++bj) { const u32x4 w = *(const u32x4*)(X1 + (size_t)row * 2048 + col0 + bj * HALF);
;                     const f32x4 x0 = {__builtin_bit_cast(float, w.x << 16), __builtin_bit_cast(float, w.x & 0xffff0000u), __builtin_bit_cast(float, w.y << 16), __builtin_bit_cast(float, w.y & 0xffff0000u)};
;                     const f32x4 x1 = {__builtin_bit_cast(float, w.z << 16), __builtin_bit_cast(float, w.z & 0xffff0000u), __builtin_bit_cast(float, w.w << 16), __builtin_bit_cast(float, w.w & 0xffff0000u)};
;                     *(f32x4*)(orow + bj * HALF) = x0 + acc[ai][bj][m][0] * r1 * gv[bj][0]; *(f32x4*)(orow + bj * HALF + 4) = x1 + acc[ai][bj][m][1] * r1 * gv[bj][1]; } }
.LBB0_692:
	s_or_b64 exec, exec, s[4:5]
	s_barrier
	global_load_dwordx4 v[136:139], v[152:153], off offset:16
	global_load_dwordx4 v[140:143], v[152:153], off
	s_waitcnt lgkmcnt(0)
	global_load_dwordx4 v[120:123], v[152:153], off offset:528
	global_load_dwordx4 v[124:127], v[152:153], off offset:512
	global_load_dword v182, v[162:163], off sc1
	v_lshlrev_b64 v[174:175], 12, v[164:165]
	v_lshl_add_u64 v[178:179], v[156:157], 0, v[174:175]
	global_load_dwordx4 v[174:177], v[178:179], off
	v_lshlrev_b64 v[180:181], 13, v[164:165]
	v_lshl_add_u64 v[180:181], v[154:155], 0, v[180:181]
	s_cmp_eq_u32 s35, 7
	s_waitcnt vmcnt(0)
	v_fmamk_f32 v165, v182, 0x3a000000, v172
	v_mul_f32_e32 v184, 0x4f800000, v165
	v_cmp_gt_f32_e32 vcc, s42, v165
	v_lshlrev_b32_e32 v182, 16, v174
	v_and_b32_e32 v183, 0xffff0000, v174
	v_cndmask_b32_e32 v165, v165, v184, vcc
	v_sqrt_f32_e32 v186, v165
	v_lshlrev_b32_e32 v174, 16, v175
	v_and_b32_e32 v175, 0xffff0000, v175
	v_lshlrev_b32_e32 v184, 16, v176
	v_add_u32_e32 v187, -1, v186
	v_add_u32_e32 v188, 1, v186
	v_fma_f32 v189, -v187, v186, v165
	v_fma_f32 v190, -v188, v186, v165
	v_cmp_ge_f32_e64 s[4:5], 0, v189
	v_and_b32_e32 v185, 0xffff0000, v176
	v_lshlrev_b32_e32 v176, 16, v177
	v_cndmask_b32_e64 v186, v186, v187, s[4:5]
	v_cmp_lt_f32_e64 s[4:5], 0, v190
	v_and_b32_e32 v177, 0xffff0000, v177
	s_nop 0
	v_cndmask_b32_e64 v186, v186, v188, s[4:5]
	v_mul_f32_e32 v187, 0x37800000, v186
	v_cndmask_b32_e32 v186, v186, v187, vcc
	v_cmp_class_f32_e32 vcc, v165, v173
	s_nop 1
	v_cndmask_b32_e32 v165, v186, v165, vcc
	v_div_scale_f32 v186, s[4:5], v165, v165, 1.0
	v_rcp_f32_e32 v187, v186
	v_div_scale_f32 v188, vcc, 1.0, v165, 1.0
	v_fma_f32 v189, -v186, v187, 1.0
	v_fmac_f32_e32 v187, v189, v187
	v_mul_f32_e32 v189, v188, v187
	v_fma_f32 v190, -v186, v189, v188
	v_fmac_f32_e32 v189, v190, v187
	v_fma_f32 v186, -v186, v189, v188
	v_div_fmas_f32 v186, v186, v187, v189
	v_div_fixup_f32 v186, v186, v165, 1.0
	v_mul_f32_e32 v132, v132, v186
	v_mul_f32_e32 v133, v133, v186
	v_mul_f32_e32 v134, v134, v186
	v_mul_f32_e32 v135, v135, v186
	v_mul_f32_e32 v188, v128, v186
	v_mul_f32_e32 v189, v129, v186
	v_mul_f32_e32 v190, v130, v186
	v_mul_f32_e32 v191, v131, v186
	v_fma_f32 v130, v142, v134, v174
	v_fma_f32 v131, v143, v135, v175
	v_fma_f32 v128, v140, v132, v182
	v_fma_f32 v129, v141, v133, v183
	v_fma_f32 v134, v138, v190, v176
	v_fma_f32 v135, v139, v191, v177
	v_fma_f32 v132, v136, v188, v184
	v_fma_f32 v133, v137, v189, v185
	global_store_dwordx4 v[180:181], v[128:131], off
	global_store_dwordx4 v[180:181], v[132:135], off offset:16
	global_load_dwordx4 v[128:131], v[178:179], off offset:256
	v_mul_f32_e32 v116, v116, v186
	v_mul_f32_e32 v117, v117, v186
	v_or_b32_e32 v132, 16, v164
	v_mul_f32_e32 v118, v118, v186
	v_mul_f32_e32 v119, v119, v186
	v_mul_f32_e32 v176, v112, v186
	v_mul_f32_e32 v177, v113, v186
	v_mul_f32_e32 v178, v114, v186
	v_mul_f32_e32 v179, v115, v186
	v_ashrrev_i32_e32 v133, 31, v132
	v_lshl_add_u64 v[134:135], v[132:133], 2, s[10:11]
	v_lshlrev_b64 v[174:175], 12, v[132:133]
	v_lshl_add_u64 v[174:175], v[156:157], 0, v[174:175]
	s_waitcnt vmcnt(0)
	v_lshlrev_b32_e32 v112, 16, v128
	v_and_b32_e32 v113, 0xffff0000, v128
	v_lshlrev_b32_e32 v114, 16, v129
	v_and_b32_e32 v115, 0xffff0000, v129
	v_lshlrev_b32_e32 v128, 16, v130
	v_and_b32_e32 v129, 0xffff0000, v130
	v_lshlrev_b32_e32 v130, 16, v131
	v_and_b32_e32 v131, 0xffff0000, v131
	v_fma_f32 v114, v126, v118, v114
	v_fma_f32 v115, v127, v119, v115
	v_fma_f32 v112, v124, v116, v112
	v_fma_f32 v113, v125, v117, v113
	v_fma_f32 v118, v122, v178, v130
	v_fma_f32 v119, v123, v179, v131
	v_fma_f32 v116, v120, v176, v128
	v_fma_f32 v117, v121, v177, v129
	global_store_dwordx4 v[180:181], v[112:115], off offset:512
	global_store_dwordx4 v[180:181], v[116:119], off offset:528
	global_load_dword v118, v[134:135], off sc1
	s_nop 0
	global_load_dwordx4 v[112:115], v[174:175], off
	v_lshlrev_b64 v[116:117], 13, v[132:133]
	v_lshl_add_u64 v[116:117], v[154:155], 0, v[116:117]
	s_waitcnt vmcnt(1)
	v_fmamk_f32 v128, v118, 0x3a000000, v172
	v_mul_f32_e32 v129, 0x4f800000, v128
	v_cmp_gt_f32_e32 vcc, s42, v128
	s_waitcnt vmcnt(0)
	v_lshlrev_b32_e32 v118, 16, v112
	v_and_b32_e32 v119, 0xffff0000, v112
	v_cndmask_b32_e32 v130, v128, v129, vcc
	v_sqrt_f32_e32 v131, v130
	v_lshlrev_b32_e32 v112, 16, v113
	v_and_b32_e32 v113, 0xffff0000, v113
	v_lshlrev_b32_e32 v128, 16, v114
	v_add_u32_e32 v132, -1, v131
	v_add_u32_e32 v133, 1, v131
	v_fma_f32 v134, -v132, v131, v130
	v_fma_f32 v135, -v133, v131, v130
	v_cmp_ge_f32_e64 s[4:5], 0, v134
	v_and_b32_e32 v129, 0xffff0000, v114
	v_lshlrev_b32_e32 v114, 16, v115
	v_cndmask_b32_e64 v131, v131, v132, s[4:5]
	v_cmp_lt_f32_e64 s[4:5], 0, v135
	v_and_b32_e32 v115, 0xffff0000, v115
	s_nop 0
	v_cndmask_b32_e64 v131, v131, v133, s[4:5]
	v_mul_f32_e32 v132, 0x37800000, v131
	v_cndmask_b32_e32 v131, v131, v132, vcc
	v_cmp_class_f32_e32 vcc, v130, v173
	s_nop 1
	v_cndmask_b32_e32 v130, v131, v130, vcc
	v_div_scale_f32 v131, s[4:5], v130, v130, 1.0
	v_rcp_f32_e32 v132, v131
	v_div_scale_f32 v133, vcc, 1.0, v130, 1.0
	v_fma_f32 v134, -v131, v132, 1.0
	v_fmac_f32_e32 v132, v134, v132
	v_mul_f32_e32 v134, v133, v132
	v_fma_f32 v135, -v131, v134, v133
	v_fmac_f32_e32 v134, v135, v132
	v_fma_f32 v131, -v131, v134, v133
	v_div_fmas_f32 v131, v131, v132, v134
	v_div_fixup_f32 v130, v131, v130, 1.0
	v_mul_f32_e32 v108, v108, v130
	v_mul_f32_e32 v109, v109, v130
	v_mul_f32_e32 v110, v110, v130
	v_mul_f32_e32 v111, v111, v130
	v_mul_f32_e32 v132, v104, v130
	v_mul_f32_e32 v133, v105, v130
	v_mul_f32_e32 v134, v106, v130
	v_mul_f32_e32 v135, v107, v130
	v_fma_f32 v106, v142, v110, v112
	v_fma_f32 v107, v143, v111, v113
	v_fma_f32 v104, v140, v108, v118
	v_fma_f32 v105, v141, v109, v119
	v_fma_f32 v110, v138, v134, v114
	v_fma_f32 v111, v139, v135, v115
	v_fma_f32 v108, v136, v132, v128
	v_fma_f32 v109, v137, v133, v129
	global_store_dwordx4 v[116:117], v[104:107], off
	global_store_dwordx4 v[116:117], v[108:111], off offset:16
	global_load_dwordx4 v[104:107], v[174:175], off offset:256
	v_mul_f32_e32 v100, v100, v130
	v_mul_f32_e32 v101, v101, v130
	v_or_b32_e32 v108, 32, v164
	v_mul_f32_e32 v102, v102, v130
	v_mul_f32_e32 v103, v103, v130
	v_mul_f32_e32 v114, v96, v130
	v_mul_f32_e32 v115, v97, v130
	v_mul_f32_e32 v118, v98, v130
	v_mul_f32_e32 v119, v99, v130
	v_ashrrev_i32_e32 v109, 31, v108
	v_lshl_add_u64 v[110:111], v[108:109], 2, s[10:11]
	v_lshlrev_b64 v[112:113], 12, v[108:109]
	v_lshl_add_u64 v[112:113], v[156:157], 0, v[112:113]
	s_waitcnt vmcnt(0)
; __device__ __forceinline__ float ld_sc1(const float* p) { return __hip_atomic_load(p, __ATOMIC_RELAXED, __HIP_MEMORY_SCOPE_AGENT); }
;     __device__ __forceinline__ void operator()(f32x4 (&acc)[2][2][4][2], const Unit& u, int wr, int wc, int fr, int fq) const {
;     ...
;         for (int ai = 0; ai < 2; ++ai)
; #pragma unroll
;             for (int m = 0; m < 4; ++m) { const int row = row0 + ai * HALF + m * 16;
;                 const float r1 = 1.f / sqrtf(ld_sc1(ss + row) * (1.f / 2048.f) + 1e-6f);
;                 float* orow = OUT + (size_t)row * 2048 + col0;
; #pragma unroll
;                 for (int bj = 0; bj < 2; ++bj) { const u32x4 w = *(const u32x4*)(X1 + (size_t)row * 2048 + col0 + bj * HALF);
;                     const f32x4 x0 = {__builtin_bit_cast(float, w.x << 16), __builtin_bit_cast(float, w.x & 0xffff0000u), __builtin_bit_cast(float, w.y << 16), __builtin_bit_cast(float, w.y & 0xffff0000u)};
;                     const f32x4 x1 = {__builtin_bit_cast(float, w.z << 16), __builtin_bit_cast(float, w.z & 0xffff0000u), __builtin_bit_cast(float, w.w << 16), __builtin_bit_cast(float, w.w & 0xffff0000u)};
;                     *(f32x4*)(orow + bj * HALF) = x0 + acc[ai][bj][m][0] * r1 * gv[bj][0]; *(f32x4*)(orow + bj * HALF + 4) = x1 + acc[ai][bj][m][1] * r1 * gv[bj][1]; } }
	v_lshlrev_b32_e32 v96, 16, v104
	v_and_b32_e32 v97, 0xffff0000, v104
	v_lshlrev_b32_e32 v98, 16, v105
	v_and_b32_e32 v99, 0xffff0000, v105
	v_lshlrev_b32_e32 v104, 16, v106
	v_and_b32_e32 v105, 0xffff0000, v106
	v_lshlrev_b32_e32 v106, 16, v107
	v_and_b32_e32 v107, 0xffff0000, v107
	v_fma_f32 v98, v126, v102, v98
	v_fma_f32 v99, v127, v103, v99
	v_fma_f32 v96, v124, v100, v96
	v_fma_f32 v97, v125, v101, v97
	v_fma_f32 v102, v122, v118, v106
	v_fma_f32 v103, v123, v119, v107
	v_fma_f32 v100, v120, v114, v104
	v_fma_f32 v101, v121, v115, v105
	global_store_dwordx4 v[116:117], v[96:99], off offset:512
	global_store_dwordx4 v[116:117], v[100:103], off offset:528
	global_load_dword v102, v[110:111], off sc1
	s_nop 0
	global_load_dwordx4 v[96:99], v[112:113], off
	v_lshlrev_b64 v[100:101], 13, v[108:109]
	v_lshl_add_u64 v[100:101], v[154:155], 0, v[100:101]
	s_waitcnt vmcnt(1)
	v_fmamk_f32 v104, v102, 0x3a000000, v172
	v_mul_f32_e32 v105, 0x4f800000, v104
	v_cmp_gt_f32_e32 vcc, s42, v104
	s_waitcnt vmcnt(0)
	v_lshlrev_b32_e32 v102, 16, v96
	v_and_b32_e32 v103, 0xffff0000, v96
	v_cndmask_b32_e32 v106, v104, v105, vcc
	v_sqrt_f32_e32 v107, v106
	v_lshlrev_b32_e32 v96, 16, v97
	v_and_b32_e32 v97, 0xffff0000, v97
	v_lshlrev_b32_e32 v104, 16, v98
	v_add_u32_e32 v108, -1, v107
	v_add_u32_e32 v109, 1, v107
	v_fma_f32 v110, -v108, v107, v106
	v_fma_f32 v111, -v109, v107, v106
	v_cmp_ge_f32_e64 s[4:5], 0, v110
	v_and_b32_e32 v105, 0xffff0000, v98
	v_lshlrev_b32_e32 v98, 16, v99
	v_cndmask_b32_e64 v107, v107, v108, s[4:5]
	v_cmp_lt_f32_e64 s[4:5], 0, v111
	v_and_b32_e32 v99, 0xffff0000, v99
	s_nop 0
	v_cndmask_b32_e64 v107, v107, v109, s[4:5]
	v_mul_f32_e32 v108, 0x37800000, v107
	v_cndmask_b32_e32 v107, v107, v108, vcc
	v_cmp_class_f32_e32 vcc, v106, v173
	s_nop 1
	v_cndmask_b32_e32 v106, v107, v106, vcc
	v_div_scale_f32 v107, s[4:5], v106, v106, 1.0
	v_rcp_f32_e32 v108, v107
	v_div_scale_f32 v109, vcc, 1.0, v106, 1.0
	v_fma_f32 v110, -v107, v108, 1.0
	v_fmac_f32_e32 v108, v110, v108
	v_mul_f32_e32 v110, v109, v108
	v_fma_f32 v111, -v107, v110, v109
	v_fmac_f32_e32 v110, v111, v108
	v_fma_f32 v107, -v107, v110, v109
	v_div_fmas_f32 v107, v107, v108, v110
	v_div_fixup_f32 v106, v107, v106, 1.0
	v_mul_f32_e32 v92, v92, v106
	v_mul_f32_e32 v93, v93, v106
	v_mul_f32_e32 v94, v94, v106
	v_mul_f32_e32 v95, v95, v106
	v_mul_f32_e32 v108, v88, v106
	v_mul_f32_e32 v109, v89, v106
	v_mul_f32_e32 v110, v90, v106
	v_mul_f32_e32 v111, v91, v106
	v_fma_f32 v90, v142, v94, v96
	v_fma_f32 v91, v143, v95, v97
	v_fma_f32 v88, v140, v92, v102
	v_fma_f32 v89, v141, v93, v103
	v_fma_f32 v94, v138, v110, v98
	v_fma_f32 v95, v139, v111, v99
	v_fma_f32 v92, v136, v108, v104
	v_fma_f32 v93, v137, v109, v105
	global_store_dwordx4 v[100:101], v[88:91], off
	global_store_dwordx4 v[100:101], v[92:95], off offset:16
	global_load_dwordx4 v[88:91], v[112:113], off offset:256
	v_mul_f32_e32 v84, v84, v106
	v_mul_f32_e32 v85, v85, v106
	v_or_b32_e32 v92, 48, v164
	v_mul_f32_e32 v86, v86, v106
	v_mul_f32_e32 v87, v87, v106
	v_mul_f32_e32 v98, v80, v106
	v_mul_f32_e32 v99, v81, v106
	v_mul_f32_e32 v102, v82, v106
	v_mul_f32_e32 v103, v83, v106
	v_ashrrev_i32_e32 v93, 31, v92
	v_lshl_add_u64 v[94:95], v[92:93], 2, s[10:11]
	v_lshlrev_b64 v[96:97], 12, v[92:93]
	v_lshl_add_u64 v[96:97], v[156:157], 0, v[96:97]
	s_waitcnt vmcnt(0)
	v_lshlrev_b32_e32 v80, 16, v88
	v_and_b32_e32 v81, 0xffff0000, v88
	v_lshlrev_b32_e32 v82, 16, v89
	v_and_b32_e32 v83, 0xffff0000, v89
	v_lshlrev_b32_e32 v88, 16, v90
	v_and_b32_e32 v89, 0xffff0000, v90
	v_lshlrev_b32_e32 v90, 16, v91
	v_and_b32_e32 v91, 0xffff0000, v91
	v_fma_f32 v82, v126, v86, v82
	v_fma_f32 v83, v127, v87, v83
	v_fma_f32 v80, v124, v84, v80
	v_fma_f32 v81, v125, v85, v81
	v_fma_f32 v86, v122, v102, v90
	v_fma_f32 v87, v123, v103, v91
	v_fma_f32 v84, v120, v98, v88
	v_fma_f32 v85, v121, v99, v89
	global_store_dwordx4 v[100:101], v[80:83], off offset:512
	global_store_dwordx4 v[100:101], v[84:87], off offset:528
	global_load_dword v86, v[94:95], off sc1
	s_nop 0
	global_load_dwordx4 v[80:83], v[96:97], off
	v_lshlrev_b64 v[84:85], 13, v[92:93]
	v_lshl_add_u64 v[84:85], v[154:155], 0, v[84:85]
	s_waitcnt vmcnt(1)
	v_fmamk_f32 v88, v86, 0x3a000000, v172
	v_mul_f32_e32 v89, 0x4f800000, v88
	v_cmp_gt_f32_e32 vcc, s42, v88
	s_waitcnt vmcnt(0)
	v_lshlrev_b32_e32 v86, 16, v80
	v_and_b32_e32 v87, 0xffff0000, v80
	v_cndmask_b32_e32 v90, v88, v89, vcc
	v_sqrt_f32_e32 v91, v90
	v_lshlrev_b32_e32 v80, 16, v81
	v_and_b32_e32 v81, 0xffff0000, v81
	v_lshlrev_b32_e32 v88, 16, v82
	v_add_u32_e32 v92, -1, v91
	v_add_u32_e32 v93, 1, v91
	v_fma_f32 v94, -v92, v91, v90
	v_fma_f32 v95, -v93, v91, v90
	v_cmp_ge_f32_e64 s[4:5], 0, v94
	v_and_b32_e32 v89, 0xffff0000, v82
	v_lshlrev_b32_e32 v82, 16, v83
	v_cndmask_b32_e64 v91, v91, v92, s[4:5]
	v_cmp_lt_f32_e64 s[4:5], 0, v95
	v_and_b32_e32 v83, 0xffff0000, v83
	s_nop 0
	v_cndmask_b32_e64 v91, v91, v93, s[4:5]
	v_mul_f32_e32 v92, 0x37800000, v91
	v_cndmask_b32_e32 v91, v91, v92, vcc
	v_cmp_class_f32_e32 vcc, v90, v173
	s_nop 1
	v_cndmask_b32_e32 v90, v91, v90, vcc
	v_div_scale_f32 v91, s[4:5], v90, v90, 1.0
	v_rcp_f32_e32 v92, v91
	v_div_scale_f32 v93, vcc, 1.0, v90, 1.0
	v_fma_f32 v94, -v91, v92, 1.0
	v_fmac_f32_e32 v92, v94, v92
	v_mul_f32_e32 v94, v93, v92
	v_fma_f32 v95, -v91, v94, v93
	v_fmac_f32_e32 v94, v95, v92
	v_fma_f32 v91, -v91, v94, v93
	v_div_fmas_f32 v91, v91, v92, v94
	v_div_fixup_f32 v90, v91, v90, 1.0
	v_mul_f32_e32 v76, v76, v90
	v_mul_f32_e32 v77, v77, v90
	v_mul_f32_e32 v78, v78, v90
	v_mul_f32_e32 v79, v79, v90
	v_mul_f32_e32 v92, v72, v90
	v_mul_f32_e32 v93, v73, v90
	v_mul_f32_e32 v94, v74, v90
	v_mul_f32_e32 v95, v75, v90
	v_fma_f32 v74, v142, v78, v80
	v_fma_f32 v75, v143, v79, v81
	v_fma_f32 v72, v140, v76, v86
	v_fma_f32 v73, v141, v77, v87
	v_fma_f32 v78, v138, v94, v82
	v_fma_f32 v79, v139, v95, v83
	v_fma_f32 v76, v136, v92, v88
	v_fma_f32 v77, v137, v93, v89
	global_store_dwordx4 v[84:85], v[72:75], off
	global_store_dwordx4 v[84:85], v[76:79], off offset:16
	global_load_dwordx4 v[72:75], v[96:97], off offset:256
	v_mul_f32_e32 v68, v68, v90
	v_mul_f32_e32 v69, v69, v90
	v_add_u32_e32 v76, 0x80, v164
	v_mul_f32_e32 v70, v70, v90
	v_mul_f32_e32 v71, v71, v90
	v_mul_f32_e32 v80, v64, v90
	v_mul_f32_e32 v81, v65, v90
	v_mul_f32_e32 v82, v66, v90
	v_mul_f32_e32 v83, v67, v90
	v_ashrrev_i32_e32 v77, 31, v76
	v_lshlrev_b64 v[78:79], 12, v[76:77]
	v_lshl_add_u64 v[78:79], v[156:157], 0, v[78:79]
	s_waitcnt vmcnt(0)
; __device__ __forceinline__ float ld_sc1(const float* p) { return __hip_atomic_load(p, __ATOMIC_RELAXED, __HIP_MEMORY_SCOPE_AGENT); }
;     __device__ __forceinline__ void operator()(f32x4 (&acc)[2][2][4][2], const Unit& u, int wr, int wc, int fr, int fq) const {
;     ...
;         for (int ai = 0; ai < 2; ++ai)
; #pragma unroll
;             for (int m = 0; m < 4; ++m) { const int row = row0 + ai * HALF + m * 16;
;                 const float r1 = 1.f / sqrtf(ld_sc1(ss + row) * (1.f / 2048.f) + 1e-6f);
;                 float* orow = OUT + (size_t)row * 2048 + col0;
; #pragma unroll
;                 for (int bj = 0; bj < 2; ++bj) { const u32x4 w = *(const u32x4*)(X1 + (size_t)row * 2048 + col0 + bj * HALF);
;                     const f32x4 x0 = {__builtin_bit_cast(float, w.x << 16), __builtin_bit_cast(float, w.x & 0xffff0000u), __builtin_bit_cast(float, w.y << 16), __builtin_bit_cast(float, w.y & 0xffff0000u)};
;                     const f32x4 x1 = {__builtin_bit_cast(float, w.z << 16), __builtin_bit_cast(float, w.z & 0xffff0000u), __builtin_bit_cast(float, w.w << 16), __builtin_bit_cast(float, w.w & 0xffff0000u)};
;                     *(f32x4*)(orow + bj * HALF) = x0 + acc[ai][bj][m][0] * r1 * gv[bj][0]; *(f32x4*)(orow + bj * HALF + 4) = x1 + acc[ai][bj][m][1] * r1 * gv[bj][1]; } }
	v_lshlrev_b32_e32 v64, 16, v72
	v_and_b32_e32 v65, 0xffff0000, v72
	v_lshlrev_b32_e32 v66, 16, v73
	v_and_b32_e32 v67, 0xffff0000, v73
	v_lshlrev_b32_e32 v72, 16, v74
	v_and_b32_e32 v73, 0xffff0000, v74
	v_lshlrev_b32_e32 v74, 16, v75
	v_and_b32_e32 v75, 0xffff0000, v75
	v_fma_f32 v66, v126, v70, v66
	v_fma_f32 v67, v127, v71, v67
	v_fma_f32 v64, v124, v68, v64
	v_fma_f32 v65, v125, v69, v65
	v_fma_f32 v70, v122, v82, v74
	v_fma_f32 v71, v123, v83, v75
	v_fma_f32 v68, v120, v80, v72
	v_fma_f32 v69, v121, v81, v73
	global_store_dwordx4 v[84:85], v[64:67], off offset:512
	global_store_dwordx4 v[84:85], v[68:71], off offset:528
	global_load_dword v70, v[162:163], off offset:512 sc1
	s_nop 0
	global_load_dwordx4 v[64:67], v[78:79], off
	v_lshlrev_b64 v[68:69], 13, v[76:77]
	v_lshl_add_u64 v[68:69], v[154:155], 0, v[68:69]
	s_waitcnt vmcnt(1)
	v_fmamk_f32 v72, v70, 0x3a000000, v172
	v_mul_f32_e32 v73, 0x4f800000, v72
	v_cmp_gt_f32_e32 vcc, s42, v72
	s_waitcnt vmcnt(0)
	v_lshlrev_b32_e32 v70, 16, v64
	v_and_b32_e32 v71, 0xffff0000, v64
	v_cndmask_b32_e32 v74, v72, v73, vcc
	v_sqrt_f32_e32 v75, v74
	v_lshlrev_b32_e32 v64, 16, v65
	v_and_b32_e32 v65, 0xffff0000, v65
	v_lshlrev_b32_e32 v72, 16, v66
	v_add_u32_e32 v76, -1, v75
	v_add_u32_e32 v77, 1, v75
	v_fma_f32 v80, -v76, v75, v74
	v_fma_f32 v81, -v77, v75, v74
	v_cmp_ge_f32_e64 s[4:5], 0, v80
	v_and_b32_e32 v73, 0xffff0000, v66
	v_lshlrev_b32_e32 v66, 16, v67
	v_cndmask_b32_e64 v75, v75, v76, s[4:5]
	v_cmp_lt_f32_e64 s[4:5], 0, v81
	v_and_b32_e32 v67, 0xffff0000, v67
	s_nop 0
	v_cndmask_b32_e64 v75, v75, v77, s[4:5]
	v_mul_f32_e32 v76, 0x37800000, v75
	v_cndmask_b32_e32 v75, v75, v76, vcc
	v_cmp_class_f32_e32 vcc, v74, v173
	s_nop 1
	v_cndmask_b32_e32 v74, v75, v74, vcc
	v_div_scale_f32 v75, s[4:5], v74, v74, 1.0
	v_rcp_f32_e32 v76, v75
	v_div_scale_f32 v77, vcc, 1.0, v74, 1.0
	v_fma_f32 v80, -v75, v76, 1.0
	v_fmac_f32_e32 v76, v80, v76
	v_mul_f32_e32 v80, v77, v76
	v_fma_f32 v81, -v75, v80, v77
	v_fmac_f32_e32 v80, v81, v76
	v_fma_f32 v75, -v75, v80, v77
	v_div_fmas_f32 v75, v75, v76, v80
	v_div_fixup_f32 v74, v75, v74, 1.0
	v_mul_f32_e32 v60, v60, v74
	v_mul_f32_e32 v61, v61, v74
	v_mul_f32_e32 v62, v62, v74
	v_mul_f32_e32 v63, v63, v74
	v_mul_f32_e32 v76, v56, v74
	v_mul_f32_e32 v77, v57, v74
	v_mul_f32_e32 v80, v58, v74
	v_mul_f32_e32 v81, v59, v74
	v_fma_f32 v58, v142, v62, v64
	v_fma_f32 v59, v143, v63, v65
	v_fma_f32 v56, v140, v60, v70
	v_fma_f32 v57, v141, v61, v71
	v_fma_f32 v62, v138, v80, v66
	v_fma_f32 v63, v139, v81, v67
	v_fma_f32 v60, v136, v76, v72
	v_fma_f32 v61, v137, v77, v73
	global_store_dwordx4 v[68:69], v[56:59], off
	global_store_dwordx4 v[68:69], v[60:63], off offset:16
	global_load_dwordx4 v[56:59], v[78:79], off offset:256
	v_mul_f32_e32 v52, v52, v74
	v_mul_f32_e32 v53, v53, v74
	v_add_u32_e32 v60, 0x90, v164
	v_mul_f32_e32 v54, v54, v74
	v_mul_f32_e32 v55, v55, v74
	v_mul_f32_e32 v64, v48, v74
	v_mul_f32_e32 v65, v49, v74
	v_mul_f32_e32 v66, v50, v74
	v_mul_f32_e32 v67, v51, v74
	v_ashrrev_i32_e32 v61, 31, v60
	v_lshlrev_b64 v[62:63], 12, v[60:61]
	v_lshl_add_u64 v[62:63], v[156:157], 0, v[62:63]
	s_waitcnt vmcnt(0)
	v_lshlrev_b32_e32 v48, 16, v56
	v_and_b32_e32 v49, 0xffff0000, v56
	v_lshlrev_b32_e32 v50, 16, v57
	v_and_b32_e32 v51, 0xffff0000, v57
	v_lshlrev_b32_e32 v56, 16, v58
	v_and_b32_e32 v57, 0xffff0000, v58
	v_lshlrev_b32_e32 v58, 16, v59
	v_and_b32_e32 v59, 0xffff0000, v59
	v_fma_f32 v50, v126, v54, v50
	v_fma_f32 v51, v127, v55, v51
	v_fma_f32 v48, v124, v52, v48
	v_fma_f32 v49, v125, v53, v49
	v_fma_f32 v54, v122, v66, v58
	v_fma_f32 v55, v123, v67, v59
	v_fma_f32 v52, v120, v64, v56
	v_fma_f32 v53, v121, v65, v57
	global_store_dwordx4 v[68:69], v[48:51], off offset:512
	global_store_dwordx4 v[68:69], v[52:55], off offset:528
	global_load_dword v54, v[162:163], off offset:576 sc1
	s_nop 0
	global_load_dwordx4 v[48:51], v[62:63], off
	v_lshlrev_b64 v[52:53], 13, v[60:61]
	v_lshl_add_u64 v[52:53], v[154:155], 0, v[52:53]
	s_waitcnt vmcnt(1)
	v_fmamk_f32 v56, v54, 0x3a000000, v172
	v_mul_f32_e32 v57, 0x4f800000, v56
	v_cmp_gt_f32_e32 vcc, s42, v56
	s_waitcnt vmcnt(0)
	v_lshlrev_b32_e32 v54, 16, v48
	v_and_b32_e32 v55, 0xffff0000, v48
	v_cndmask_b32_e32 v58, v56, v57, vcc
	v_sqrt_f32_e32 v59, v58
	v_lshlrev_b32_e32 v48, 16, v49
	v_and_b32_e32 v49, 0xffff0000, v49
	v_lshlrev_b32_e32 v56, 16, v50
	v_add_u32_e32 v60, -1, v59
	v_add_u32_e32 v61, 1, v59
	v_fma_f32 v64, -v60, v59, v58
	v_fma_f32 v65, -v61, v59, v58
	v_cmp_ge_f32_e64 s[4:5], 0, v64
	v_and_b32_e32 v57, 0xffff0000, v50
	v_lshlrev_b32_e32 v50, 16, v51
	v_cndmask_b32_e64 v59, v59, v60, s[4:5]
	v_cmp_lt_f32_e64 s[4:5], 0, v65
	v_and_b32_e32 v51, 0xffff0000, v51
	s_nop 0
	v_cndmask_b32_e64 v59, v59, v61, s[4:5]
	v_mul_f32_e32 v60, 0x37800000, v59
	v_cndmask_b32_e32 v59, v59, v60, vcc
	v_cmp_class_f32_e32 vcc, v58, v173
	s_nop 1
	v_cndmask_b32_e32 v58, v59, v58, vcc
	v_div_scale_f32 v59, s[4:5], v58, v58, 1.0
	v_rcp_f32_e32 v60, v59
	v_div_scale_f32 v61, vcc, 1.0, v58, 1.0
	v_fma_f32 v64, -v59, v60, 1.0
	v_fmac_f32_e32 v60, v64, v60
	v_mul_f32_e32 v64, v61, v60
	v_fma_f32 v65, -v59, v64, v61
	v_fmac_f32_e32 v64, v65, v60
	v_fma_f32 v59, -v59, v64, v61
	v_div_fmas_f32 v59, v59, v60, v64
	v_div_fixup_f32 v58, v59, v58, 1.0
	v_mul_f32_e32 v44, v44, v58
	v_mul_f32_e32 v45, v45, v58
	v_mul_f32_e32 v46, v46, v58
	v_mul_f32_e32 v47, v47, v58
	v_mul_f32_e32 v60, v40, v58
	v_mul_f32_e32 v61, v41, v58
	v_mul_f32_e32 v64, v42, v58
	v_mul_f32_e32 v65, v43, v58
	v_fma_f32 v42, v142, v46, v48
	v_fma_f32 v43, v143, v47, v49
	v_fma_f32 v40, v140, v44, v54
	v_fma_f32 v41, v141, v45, v55
	v_fma_f32 v46, v138, v64, v50
	v_fma_f32 v47, v139, v65, v51
	v_fma_f32 v44, v136, v60, v56
	v_fma_f32 v45, v137, v61, v57
	global_store_dwordx4 v[52:53], v[40:43], off
	global_store_dwordx4 v[52:53], v[44:47], off offset:16
	global_load_dwordx4 v[40:43], v[62:63], off offset:256
	v_mul_f32_e32 v36, v36, v58
	v_mul_f32_e32 v37, v37, v58
	v_add_u32_e32 v44, 0xa0, v164
	v_mul_f32_e32 v38, v38, v58
	v_mul_f32_e32 v39, v39, v58
	v_mul_f32_e32 v48, v32, v58
	v_mul_f32_e32 v49, v33, v58
	v_mul_f32_e32 v50, v34, v58
	v_mul_f32_e32 v51, v35, v58
	v_ashrrev_i32_e32 v45, 31, v44
	v_lshlrev_b64 v[46:47], 12, v[44:45]
	v_lshl_add_u64 v[46:47], v[156:157], 0, v[46:47]
	s_waitcnt vmcnt(0)
; __device__ __forceinline__ float ld_sc1(const float* p) { return __hip_atomic_load(p, __ATOMIC_RELAXED, __HIP_MEMORY_SCOPE_AGENT); }
;     __device__ __forceinline__ void operator()(f32x4 (&acc)[2][2][4][2], const Unit& u, int wr, int wc, int fr, int fq) const {
;     ...
;         for (int ai = 0; ai < 2; ++ai)
; #pragma unroll
;             for (int m = 0; m < 4; ++m) { const int row = row0 + ai * HALF + m * 16;
;                 const float r1 = 1.f / sqrtf(ld_sc1(ss + row) * (1.f / 2048.f) + 1e-6f);
;                 float* orow = OUT + (size_t)row * 2048 + col0;
; #pragma unroll
;                 for (int bj = 0; bj < 2; ++bj) { const u32x4 w = *(const u32x4*)(X1 + (size_t)row * 2048 + col0 + bj * HALF);
;                     const f32x4 x0 = {__builtin_bit_cast(float, w.x << 16), __builtin_bit_cast(float, w.x & 0xffff0000u), __builtin_bit_cast(float, w.y << 16), __builtin_bit_cast(float, w.y & 0xffff0000u)};
;                     const f32x4 x1 = {__builtin_bit_cast(float, w.z << 16), __builtin_bit_cast(float, w.z & 0xffff0000u), __builtin_bit_cast(float, w.w << 16), __builtin_bit_cast(float, w.w & 0xffff0000u)};
;                     *(f32x4*)(orow + bj * HALF) = x0 + acc[ai][bj][m][0] * r1 * gv[bj][0]; *(f32x4*)(orow + bj * HALF + 4) = x1 + acc[ai][bj][m][1] * r1 * gv[bj][1]; } }
	v_lshlrev_b32_e32 v32, 16, v40
	v_and_b32_e32 v33, 0xffff0000, v40
	v_lshlrev_b32_e32 v34, 16, v41
	v_and_b32_e32 v35, 0xffff0000, v41
	v_lshlrev_b32_e32 v40, 16, v42
	v_and_b32_e32 v41, 0xffff0000, v42
	v_lshlrev_b32_e32 v42, 16, v43
	v_and_b32_e32 v43, 0xffff0000, v43
	v_fma_f32 v34, v126, v38, v34
	v_fma_f32 v35, v127, v39, v35
	v_fma_f32 v32, v124, v36, v32
	v_fma_f32 v33, v125, v37, v33
	v_fma_f32 v38, v122, v50, v42
	v_fma_f32 v39, v123, v51, v43
	v_fma_f32 v36, v120, v48, v40
	v_fma_f32 v37, v121, v49, v41
	global_store_dwordx4 v[52:53], v[32:35], off offset:512
	global_store_dwordx4 v[52:53], v[36:39], off offset:528
	global_load_dword v38, v[162:163], off offset:640 sc1
	s_nop 0
	global_load_dwordx4 v[32:35], v[46:47], off
	v_lshlrev_b64 v[36:37], 13, v[44:45]
	v_lshl_add_u64 v[36:37], v[154:155], 0, v[36:37]
	s_waitcnt vmcnt(1)
	v_fmamk_f32 v40, v38, 0x3a000000, v172
	v_mul_f32_e32 v41, 0x4f800000, v40
	v_cmp_gt_f32_e32 vcc, s42, v40
	s_waitcnt vmcnt(0)
	v_lshlrev_b32_e32 v38, 16, v32
	v_and_b32_e32 v39, 0xffff0000, v32
	v_cndmask_b32_e32 v42, v40, v41, vcc
	v_sqrt_f32_e32 v43, v42
	v_lshlrev_b32_e32 v32, 16, v33
	v_and_b32_e32 v33, 0xffff0000, v33
	v_lshlrev_b32_e32 v40, 16, v34
	v_add_u32_e32 v44, -1, v43
	v_add_u32_e32 v45, 1, v43
	v_fma_f32 v48, -v44, v43, v42
	v_fma_f32 v49, -v45, v43, v42
	v_cmp_ge_f32_e64 s[4:5], 0, v48
	v_and_b32_e32 v41, 0xffff0000, v34
	v_lshlrev_b32_e32 v34, 16, v35
	v_cndmask_b32_e64 v43, v43, v44, s[4:5]
	v_cmp_lt_f32_e64 s[4:5], 0, v49
	v_and_b32_e32 v35, 0xffff0000, v35
	s_nop 0
	v_cndmask_b32_e64 v43, v43, v45, s[4:5]
	v_mul_f32_e32 v44, 0x37800000, v43
	v_cndmask_b32_e32 v43, v43, v44, vcc
	v_cmp_class_f32_e32 vcc, v42, v173
	s_nop 1
	v_cndmask_b32_e32 v42, v43, v42, vcc
	v_div_scale_f32 v43, s[4:5], v42, v42, 1.0
	v_rcp_f32_e32 v44, v43
	v_div_scale_f32 v45, vcc, 1.0, v42, 1.0
	v_fma_f32 v48, -v43, v44, 1.0
	v_fmac_f32_e32 v44, v48, v44
	v_mul_f32_e32 v48, v45, v44
	v_fma_f32 v49, -v43, v48, v45
	v_fmac_f32_e32 v48, v49, v44
	v_fma_f32 v43, -v43, v48, v45
	v_div_fmas_f32 v43, v43, v44, v48
	v_div_fixup_f32 v42, v43, v42, 1.0
	v_mul_f32_e32 v28, v28, v42
	v_mul_f32_e32 v29, v29, v42
	v_mul_f32_e32 v30, v30, v42
	v_mul_f32_e32 v31, v31, v42
	v_mul_f32_e32 v44, v24, v42
	v_mul_f32_e32 v45, v25, v42
	v_mul_f32_e32 v48, v26, v42
	v_mul_f32_e32 v49, v27, v42
	v_fma_f32 v26, v142, v30, v32
	v_fma_f32 v27, v143, v31, v33
	v_fma_f32 v24, v140, v28, v38
	v_fma_f32 v25, v141, v29, v39
	v_fma_f32 v30, v138, v48, v34
	v_fma_f32 v31, v139, v49, v35
	v_fma_f32 v28, v136, v44, v40
	v_fma_f32 v29, v137, v45, v41
	global_store_dwordx4 v[36:37], v[24:27], off
	global_store_dwordx4 v[36:37], v[28:31], off offset:16
	global_load_dwordx4 v[24:27], v[46:47], off offset:256
	v_mul_f32_e32 v20, v20, v42
	v_mul_f32_e32 v21, v21, v42
	v_add_u32_e32 v28, 0xb0, v164
	v_mul_f32_e32 v22, v22, v42
	v_mul_f32_e32 v23, v23, v42
	v_mul_f32_e32 v32, v16, v42
	v_mul_f32_e32 v33, v17, v42
	v_mul_f32_e32 v34, v18, v42
	v_mul_f32_e32 v35, v19, v42
	v_ashrrev_i32_e32 v29, 31, v28
	v_lshlrev_b64 v[30:31], 12, v[28:29]
	v_lshl_add_u64 v[30:31], v[156:157], 0, v[30:31]
	s_waitcnt vmcnt(0)
	v_lshlrev_b32_e32 v16, 16, v24
	v_and_b32_e32 v17, 0xffff0000, v24
	v_lshlrev_b32_e32 v18, 16, v25
	v_and_b32_e32 v19, 0xffff0000, v25
	v_lshlrev_b32_e32 v24, 16, v26
	v_and_b32_e32 v25, 0xffff0000, v26
	v_lshlrev_b32_e32 v26, 16, v27
	v_and_b32_e32 v27, 0xffff0000, v27
	v_fma_f32 v18, v126, v22, v18
	v_fma_f32 v19, v127, v23, v19
	v_fma_f32 v16, v124, v20, v16
	v_fma_f32 v17, v125, v21, v17
	v_fma_f32 v22, v122, v34, v26
	v_fma_f32 v23, v123, v35, v27
	v_fma_f32 v20, v120, v32, v24
	v_fma_f32 v21, v121, v33, v25
	global_store_dwordx4 v[36:37], v[16:19], off offset:512
	global_store_dwordx4 v[36:37], v[20:23], off offset:528
	global_load_dword v22, v[162:163], off offset:704 sc1
	s_nop 0
	global_load_dwordx4 v[16:19], v[30:31], off
	v_lshlrev_b64 v[20:21], 13, v[28:29]
	v_lshl_add_u64 v[20:21], v[154:155], 0, v[20:21]
	s_waitcnt vmcnt(1)
	v_fmamk_f32 v24, v22, 0x3a000000, v172
	v_mul_f32_e32 v25, 0x4f800000, v24
	v_cmp_gt_f32_e32 vcc, s42, v24
	s_waitcnt vmcnt(0)
	v_lshlrev_b32_e32 v22, 16, v16
	v_and_b32_e32 v23, 0xffff0000, v16
	v_cndmask_b32_e32 v26, v24, v25, vcc
	v_sqrt_f32_e32 v27, v26
	v_lshlrev_b32_e32 v16, 16, v17
	v_and_b32_e32 v17, 0xffff0000, v17
	v_lshlrev_b32_e32 v24, 16, v18
	v_add_u32_e32 v28, -1, v27
	v_add_u32_e32 v29, 1, v27
	v_fma_f32 v32, -v28, v27, v26
	v_fma_f32 v33, -v29, v27, v26
	v_cmp_ge_f32_e64 s[4:5], 0, v32
	v_and_b32_e32 v25, 0xffff0000, v18
	v_lshlrev_b32_e32 v18, 16, v19
	v_cndmask_b32_e64 v27, v27, v28, s[4:5]
	v_cmp_lt_f32_e64 s[4:5], 0, v33
	v_and_b32_e32 v19, 0xffff0000, v19
	s_nop 0
	v_cndmask_b32_e64 v27, v27, v29, s[4:5]
	v_mul_f32_e32 v28, 0x37800000, v27
	v_cndmask_b32_e32 v27, v27, v28, vcc
	v_cmp_class_f32_e32 vcc, v26, v173
	s_nop 1
	v_cndmask_b32_e32 v26, v27, v26, vcc
	v_div_scale_f32 v27, s[4:5], v26, v26, 1.0
	v_rcp_f32_e32 v28, v27
	v_div_scale_f32 v29, vcc, 1.0, v26, 1.0
	s_mov_b64 s[4:5], -1
	v_fma_f32 v32, -v27, v28, 1.0
	v_fmac_f32_e32 v28, v32, v28
	v_mul_f32_e32 v32, v29, v28
	v_fma_f32 v33, -v27, v32, v29
	v_fmac_f32_e32 v32, v33, v28
	v_fma_f32 v27, -v27, v32, v29
	v_div_fmas_f32 v27, v27, v28, v32
	v_div_fixup_f32 v26, v27, v26, 1.0
	v_mul_f32_e32 v12, v12, v26
	v_mul_f32_e32 v13, v13, v26
	v_mul_f32_e32 v14, v14, v26
	v_mul_f32_e32 v15, v15, v26
	v_mul_f32_e32 v28, v8, v26
	v_mul_f32_e32 v29, v9, v26
	v_mul_f32_e32 v32, v10, v26
	v_mul_f32_e32 v33, v11, v26
	v_fma_f32 v10, v142, v14, v16
	v_fma_f32 v11, v143, v15, v17
	v_fma_f32 v8, v140, v12, v22
	v_fma_f32 v9, v141, v13, v23
	v_fma_f32 v14, v138, v32, v18
	v_fma_f32 v15, v139, v33, v19
	v_fma_f32 v12, v136, v28, v24
	v_fma_f32 v13, v137, v29, v25
	global_store_dwordx4 v[20:21], v[8:11], off
	global_store_dwordx4 v[20:21], v[12:15], off offset:16
	global_load_dwordx4 v[8:11], v[30:31], off offset:256
	v_mul_f32_e32 v4, v4, v26
	v_mul_f32_e32 v5, v5, v26
	v_mul_f32_e32 v6, v6, v26
	v_mul_f32_e32 v7, v7, v26
	v_mul_f32_e32 v12, v0, v26
	v_mul_f32_e32 v13, v1, v26
	v_mul_f32_e32 v14, v2, v26
	v_mul_f32_e32 v15, v3, v26
	s_waitcnt vmcnt(0)
	v_lshlrev_b32_e32 v0, 16, v8
	v_and_b32_e32 v1, 0xffff0000, v8
	v_lshlrev_b32_e32 v2, 16, v9
	v_and_b32_e32 v3, 0xffff0000, v9
	v_lshlrev_b32_e32 v8, 16, v10
	v_and_b32_e32 v9, 0xffff0000, v10
	v_lshlrev_b32_e32 v10, 16, v11
	v_and_b32_e32 v11, 0xffff0000, v11
	v_fma_f32 v2, v126, v6, v2
	v_fma_f32 v3, v127, v7, v3
	v_fma_f32 v0, v124, v4, v0
	v_fma_f32 v1, v125, v5, v1
	v_fma_f32 v6, v122, v14, v10
	v_fma_f32 v7, v123, v15, v11
	v_fma_f32 v4, v120, v12, v8
	v_fma_f32 v5, v121, v13, v9
	global_store_dwordx4 v[20:21], v[0:3], off offset:512
	global_store_dwordx4 v[20:21], v[4:7], off offset:528
	s_cbranch_scc1 .LBB0_655
	s_andn2_b64 vcc, exec, s[8:9]
	s_cbranch_vccnz .LBB0_654
	s_barrier
	s_branch .LBB0_654
